# nt loads for the read-once SGU inputs (zu, zv) in P2 on top of v61
# speedup vs baseline: 1.0583x; 1.0089x over previous
.LBB0_416:
	ds_bpermute_b32 v0, v129, v133
	s_waitcnt vmcnt(7)
	v_mov_b32_e32 v6, v172
	v_mov_b32_e32 v41, v2
	v_mov_b32_e32 v37, v2
	v_mov_b32_e32 v61, v2
	s_waitcnt lgkmcnt(0)
	v_add_f32_e32 v0, v133, v0
	ds_bpermute_b32 v1, v131, v0
	s_waitcnt lgkmcnt(0)
	v_add_f32_e32 v3, v0, v1
	s_load_dwordx2 s[6:7], s[0:1], 0xb0
	s_load_dwordx4 s[8:11], s[0:1], 0x28
	s_load_dwordx2 s[20:21], s[0:1], 0x40
	v_readfirstlane_b32 s12, v6
	s_ashr_i32 s18, s12, 6
	s_waitcnt lgkmcnt(0)
	s_add_u32 s14, s6, 0xb800000
	s_addc_u32 s15, s7, 0
	s_add_u32 s12, s6, 0x1b00000
	s_addc_u32 s13, s7, 0
	s_lshl_b32 s16, s18, 4
	v_and_b32_e32 v98, 15, v6
	s_ashr_i32 s17, s16, 31
	v_or_b32_e32 v0, s16, v98
	v_mov_b32_e32 v1, s17
	s_add_u32 s19, s60, s16
	v_lshlrev_b64 v[4:5], 8, v[0:1]
	s_addc_u32 s22, s61, s17
	v_lshl_add_u64 v[4:5], s[12:13], 0, v[4:5]
	v_and_b32_e32 v40, 48, v6
	s_add_u32 s23, s16, 0x80
	v_lshl_add_u64 v[4:5], v[4:5], 0, v[40:41]
	s_addc_u32 s24, s17, 0
	global_load_dwordx4 v[32:35], v[4:5], off
	global_load_dwordx4 v[28:31], v[4:5], off offset:64
	global_load_dwordx4 v[24:27], v[4:5], off offset:128
	global_load_dwordx4 v[20:23], v[4:5], off offset:192
	v_or_b32_e32 v4, s23, v98
	v_mov_b32_e32 v5, s24
	v_lshlrev_b64 v[4:5], 8, v[4:5]
	v_lshl_add_u64 v[4:5], s[12:13], 0, v[4:5]
	v_ashrrev_i32_e32 v1, 31, v0
	v_lshl_add_u64 v[4:5], v[4:5], 0, v[40:41]
	v_lshl_add_u64 v[0:1], v[0:1], 2, s[20:21]
	v_and_b32_e32 v97, 63, v6
	v_bfe_u32 v70, v6, 4, 2
	global_load_dwordx4 v[16:19], v[4:5], off
	global_load_dwordx4 v[12:15], v[4:5], off offset:64
	global_load_dwordx4 v[8:11], v[4:5], off offset:128
	s_nop 0
	global_load_dwordx4 v[4:7], v[4:5], off offset:192
	s_nop 0
	global_load_dword v231, v[0:1], off
	global_load_dword v41, v[0:1], off offset:512
	global_load_dword v167, v[0:1], off offset:1024
	global_load_dword v166, v[0:1], off offset:1536
	global_load_dword v137, v[0:1], off offset:2048
	global_load_dword v135, v[0:1], off offset:2560
	global_load_dword v133, v[0:1], off offset:3072
	global_load_dword v99, v[0:1], off offset:3584
	v_or_b32_e32 v0, s19, v98
	v_mov_b64_e32 v[38:39], s[14:15]
	v_mad_u64_u32 v[38:39], s[20:21], v0, s66, v[38:39]
	s_mul_i32 s20, s22, 0xe00
	v_lshlrev_b32_e32 v36, 3, v70
	v_add_u32_e32 v39, s20, v39
	v_lshl_add_u64 v[58:59], v[38:39], 0, v[36:37]
	v_lshlrev_b32_e32 v1, 2, v97
	global_load_dwordx2 v[56:57], v[58:59], off offset:1536 nt
	global_load_dwordx2 v[54:55], v[58:59], off offset:1568 nt
	global_load_dwordx2 v[52:53], v[58:59], off offset:1600 nt
	global_load_dwordx2 v[50:51], v[58:59], off offset:1632 nt
	global_load_dwordx2 v[48:49], v[58:59], off offset:1664 nt
	global_load_dwordx2 v[46:47], v[58:59], off offset:1696 nt
	global_load_dwordx2 v[44:45], v[58:59], off offset:1728 nt
	global_load_dwordx2 v[42:43], v[58:59], off offset:1760 nt
	global_load_dwordx2 v[114:115], v[58:59], off offset:1792 nt
	global_load_dwordx2 v[112:113], v[58:59], off offset:1824 nt
	global_load_dwordx2 v[110:111], v[58:59], off offset:1856 nt
	global_load_dwordx2 v[108:109], v[58:59], off offset:1888 nt
	global_load_dwordx2 v[106:107], v[58:59], off offset:1920 nt
	global_load_dwordx2 v[104:105], v[58:59], off offset:1952 nt
	global_load_dwordx2 v[102:103], v[58:59], off offset:1984 nt
	global_load_dwordx2 v[100:101], v[58:59], off offset:2016 nt
	s_barrier
	global_load_dword v37, v1, s[8:9]
	global_load_dword v138, v1, s[10:11]
	global_load_dword v139, v1, s[8:9] offset:256
	global_load_dword v140, v1, s[10:11] offset:256
	global_load_dword v141, v1, s[8:9] offset:512
	global_load_dword v142, v1, s[10:11] offset:512
	global_load_dword v143, v1, s[8:9] offset:768
	global_load_dword v144, v1, s[10:11] offset:768
	global_load_dword v145, v1, s[8:9] offset:1024
	global_load_dword v146, v1, s[10:11] offset:1024
	global_load_dword v147, v1, s[8:9] offset:1280
	global_load_dword v148, v1, s[10:11] offset:1280
	global_load_dword v149, v1, s[8:9] offset:1536
	global_load_dword v150, v1, s[10:11] offset:1536
	global_load_dword v151, v1, s[8:9] offset:1792
	global_load_dword v152, v1, s[10:11] offset:1792
	s_mul_hi_u32 s8, s19, 0xe00
	s_add_i32 s9, s8, s20
	s_mulk_i32 s19, 0xe00
	s_add_u32 s8, s14, s19
	s_addc_u32 s9, s15, s9
	v_lshlrev_b32_e32 v60, 1, v97
	v_lshl_add_u64 v[38:39], s[8:9], 0, v[60:61]
	v_lshl_add_u64 v[62:63], v[38:39], 0, s[52:53]
	v_add_co_u32_e32 v64, vcc, s93, v38
	v_mov_b32_e32 v1, s22
	s_nop 0
	v_addc_co_u32_e32 v65, vcc, 0, v39, vcc
	global_load_ushort v61, v[62:63], off offset:3584 nt
	global_load_ushort v71, v[62:63], off offset:3840 nt
	global_load_ushort v72, v[62:63], off offset:3968 nt
	global_load_ushort v73, v[64:65], off offset:2560 nt
	global_load_ushort v74, v[64:65], off offset:2688 nt
	global_load_ushort v75, v[64:65], off offset:2816 nt
	v_add_co_u32_e32 v66, vcc, s94, v38
	v_lshlrev_b32_e32 v96, 2, v70
	s_nop 0
	v_addc_co_u32_e32 v67, vcc, 0, v39, vcc
	v_add_co_u32_e32 v68, vcc, s95, v38
	s_nop 1
	v_addc_co_u32_e32 v69, vcc, 0, v39, vcc
	global_load_ushort v76, v[68:69], off offset:1280 nt
	global_load_ushort v77, v[68:69], off offset:1408 nt
	global_load_ushort v78, v[68:69], off offset:1664 nt
	global_load_ushort v79, v[68:69], off offset:1792 nt
	global_load_ushort v160, v[68:69], off offset:1920 nt
	global_load_ushort v80, v[68:69], off offset:1536 nt
	global_load_ushort v81, v[68:69], off offset:1024 nt
	global_load_ushort v83, v[66:67], off offset:1536 nt
	global_load_ushort v84, v[66:67], off offset:1792 nt
	global_load_ushort v82, v[66:67], off offset:1920 nt
	global_load_ushort v85, v[66:67], off offset:2048 nt
	global_load_ushort v87, v[66:67], off offset:2176 nt
	global_load_ushort v89, v[66:67], off offset:2304 nt
	global_load_ushort v90, v60, s[8:9] offset:2560 nt
	global_load_ushort v153, v60, s[8:9] offset:2688 nt
	global_load_ushort v91, v60, s[8:9] offset:2816 nt
	global_load_ushort v92, v60, s[8:9] offset:2944 nt
	global_load_ushort v93, v60, s[8:9] offset:3200 nt
	global_load_ushort v94, v60, s[8:9] offset:3328 nt
	global_load_ushort v95, v60, s[8:9] offset:3072 nt
	global_load_ushort v156, v60, s[8:9] offset:3456 nt
	global_load_ushort v161, v[64:65], off offset:2944 nt
	global_load_ushort v158, v[62:63], off offset:3712 nt
	global_load_ushort v163, v[66:67], off offset:2432 nt
	global_load_ushort v162, v[66:67], off offset:1664 nt
	global_load_ushort v165, v[68:69], off offset:1152 nt
	v_xor_b32_e32 v60, 1, v223
	v_cmp_lt_i32_e32 vcc, v60, v227
	s_lshl_b32 s9, s18, 5
	s_add_i32 s9, s9, 0
	v_cndmask_b32_e32 v60, v223, v60, vcc
	v_lshlrev_b32_e32 v154, 2, v60
	v_xor_b32_e32 v60, 2, v223
	v_cmp_lt_i32_e32 vcc, v60, v227
	s_mov_b32 s8, 4
	s_waitcnt vmcnt(20)
	v_perm_b32 v88, v77, v80, s67
	v_cndmask_b32_e32 v60, v223, v60, vcc
	v_lshlrev_b32_e32 v155, 2, v60
	v_xor_b32_e32 v60, 4, v223
	v_cmp_lt_i32_e32 vcc, v60, v227
	s_waitcnt vmcnt(19)
	v_perm_b32 v86, v81, v76, s67
	s_waitcnt vmcnt(15)
	v_perm_b32 v82, v82, v85, s67
	v_cndmask_b32_e32 v60, v223, v60, vcc
	v_lshlrev_b32_e32 v157, 2, v60
	v_xor_b32_e32 v60, 8, v223
	v_cmp_lt_i32_e32 vcc, v60, v227
	v_perm_b32 v64, v74, v75, s67
	v_perm_b32 v74, v61, v71, s67
	v_cndmask_b32_e32 v60, v223, v60, vcc
	v_mov_b32_e32 v61, s9
	v_lshlrev_b32_e32 v159, 2, v60
	v_perm_b32 v60, v78, v79, s67
	s_waitcnt vmcnt(13)
	v_perm_b32 v62, v87, v89, s67
	v_perm_b32 v80, v83, v84, s67
	v_perm_b32 v76, v72, v73, s67
	s_waitcnt vmcnt(7)
	v_perm_b32 v66, v93, v94, s67
	s_waitcnt vmcnt(6)
	v_perm_b32 v70, v92, v95, s67
	v_perm_b32 v68, v90, v91, s67
	v_mad_u32_u24 v164, v97, s96, v61
	s_movk_i32 s9, 0xffe0
.LBB0_417:
	s_and_b32 s10, s8, 12
	s_mul_i32 s36, s10, 0xe00
	v_lshl_add_u64 v[72:73], v[38:39], 0, s[36:37]
	v_lshl_add_u64 v[78:79], v[72:73], 0, s[52:53]
	v_lshlrev_b32_e32 v253, 16, v153
	s_waitcnt vmcnt(5)
	v_lshlrev_b32_e32 v67, 16, v156
	s_waitcnt vmcnt(3)
	v_lshlrev_b32_e32 v252, 16, v158
	global_load_ushort v225, v[72:73], off offset:2560 nt
	global_load_ushort v153, v[72:73], off offset:2688 nt
	global_load_ushort v226, v[72:73], off offset:2816 nt
	global_load_ushort v227, v[72:73], off offset:2944 nt
	global_load_ushort v228, v[72:73], off offset:3072 nt
	global_load_ushort v229, v[72:73], off offset:3200 nt
	global_load_ushort v230, v[72:73], off offset:3328 nt
	global_load_ushort v156, v[72:73], off offset:3456 nt
	global_load_ushort v232, v[78:79], off offset:3584 nt
	global_load_ushort v158, v[78:79], off offset:3712 nt
	global_load_ushort v233, v[78:79], off offset:3840 nt
	global_load_ushort v234, v[78:79], off offset:3968 nt
	v_add_co_u32_e32 v78, vcc, s93, v72
	v_lshlrev_b32_e32 v65, 16, v161
	s_nop 0
	v_addc_co_u32_e32 v79, vcc, 0, v73, vcc
	global_load_ushort v235, v[78:79], off offset:2560 nt
	global_load_ushort v236, v[78:79], off offset:2688 nt
	global_load_ushort v237, v[78:79], off offset:2816 nt
	global_load_ushort v161, v[78:79], off offset:2944 nt
	v_add_co_u32_e32 v78, vcc, s94, v72
	v_and_b32_e32 v69, 0xffff0000, v68
	s_nop 0
	v_addc_co_u32_e32 v79, vcc, 0, v73, vcc
	v_add_co_u32_e32 v72, vcc, s95, v72
	v_lshlrev_b32_e32 v68, 16, v68
	s_nop 0
	v_addc_co_u32_e32 v73, vcc, 0, v73, vcc
	s_waitcnt vmcnt(17)
	v_lshlrev_b32_e32 v251, 16, v162
	v_lshlrev_b32_e32 v63, 16, v163
	s_waitcnt vmcnt(16)
	v_lshlrev_b32_e32 v250, 16, v165
	v_lshlrev_b32_e32 v61, 16, v160
	global_load_ushort v238, v[78:79], off offset:1536 nt
	global_load_ushort v162, v[78:79], off offset:1664 nt
	global_load_ushort v239, v[78:79], off offset:1792 nt
	global_load_ushort v240, v[78:79], off offset:1920 nt
	global_load_ushort v241, v[78:79], off offset:2048 nt
	global_load_ushort v242, v[78:79], off offset:2176 nt
	global_load_ushort v243, v[78:79], off offset:2304 nt
	global_load_ushort v163, v[78:79], off offset:2432 nt
	global_load_ushort v244, v[72:73], off offset:1024 nt
	global_load_ushort v165, v[72:73], off offset:1152 nt
	global_load_ushort v245, v[72:73], off offset:1280 nt
	global_load_ushort v246, v[72:73], off offset:1408 nt
	global_load_ushort v247, v[72:73], off offset:1536 nt
	global_load_ushort v248, v[72:73], off offset:1664 nt
	global_load_ushort v249, v[72:73], off offset:1792 nt
	global_load_ushort v160, v[72:73], off offset:1920 nt
	v_add_f32_e32 v71, 0, v69
	v_pk_mul_f32 v[72:73], v[68:69], v[68:69]
	v_add_f32_e32 v71, v71, v253
	v_fma_f32 v73, v253, v253, v73
	v_add_f32_e32 v71, v71, v68
	v_add_f32_e32 v75, v72, v73
	v_and_b32_e32 v73, 0xffff0000, v70
	v_lshlrev_b32_e32 v72, 16, v70
	v_add_f32_e32 v77, v71, v73
	v_pk_mul_f32 v[70:71], v[72:73], v[72:73]
	v_mul_f32_e32 v92, v67, v67
	v_add_f32_e32 v71, v71, v75
	v_add_f32_e32 v75, v77, v72
	v_add_f32_e32 v77, v70, v71
	v_and_b32_e32 v71, 0xffff0000, v66
	v_lshlrev_b32_e32 v70, 16, v66
	v_pk_mul_f32 v[78:79], v[70:71], v[70:71]
	v_add_f32_e32 v66, v75, v71
	v_add_f32_e32 v75, v79, v77
	v_add_f32_e32 v93, v66, v70
	v_add_f32_e32 v66, v78, v75
	v_and_b32_e32 v75, 0xffff0000, v74
	v_lshlrev_b32_e32 v74, 16, v74
	v_add_f32_e32 v77, 0, v75
	v_pk_mul_f32 v[78:79], v[74:75], v[74:75]
	v_add_f32_e32 v77, v77, v252
	v_fma_f32 v79, v252, v252, v79
	v_add_f32_e32 v77, v77, v74
	v_add_f32_e32 v81, v78, v79
	v_and_b32_e32 v79, 0xffff0000, v76
	v_lshlrev_b32_e32 v78, 16, v76
	v_add_f32_e32 v83, v77, v79
	v_pk_mul_f32 v[76:77], v[78:79], v[78:79]
	v_pk_add_f32 v[92:93], v[92:93], v[66:67]
	v_add_f32_e32 v77, v77, v81
	v_add_f32_e32 v81, v83, v78
	v_add_f32_e32 v83, v76, v77
	v_and_b32_e32 v77, 0xffff0000, v64
	v_lshlrev_b32_e32 v76, 16, v64
	v_pk_mul_f32 v[84:85], v[76:77], v[76:77]
	v_add_f32_e32 v64, v81, v77
	v_add_f32_e32 v81, v85, v83
	v_add_f32_e32 v95, v64, v76
	v_add_f32_e32 v64, v84, v81
	v_and_b32_e32 v81, 0xffff0000, v80
	v_lshlrev_b32_e32 v80, 16, v80
	v_add_f32_e32 v83, 0, v81
	v_pk_mul_f32 v[84:85], v[80:81], v[80:81]
	v_add_f32_e32 v83, v83, v251
	v_fma_f32 v85, v251, v251, v85
	v_add_f32_e32 v83, v83, v80
	v_add_f32_e32 v87, v84, v85
	v_and_b32_e32 v85, 0xffff0000, v82
	v_lshlrev_b32_e32 v84, 16, v82
	v_add_f32_e32 v89, v83, v85
	v_pk_mul_f32 v[82:83], v[84:85], v[84:85]
	ds_bpermute_b32 v121, v154, v93
	v_add_f32_e32 v83, v83, v87
	v_add_f32_e32 v87, v89, v84
	v_add_f32_e32 v89, v82, v83
	v_and_b32_e32 v83, 0xffff0000, v62
	v_lshlrev_b32_e32 v82, 16, v62
	v_pk_mul_f32 v[90:91], v[82:83], v[82:83]
	v_add_f32_e32 v62, v87, v83
	v_add_f32_e32 v87, v91, v89
	v_add_f32_e32 v117, v62, v82
	v_add_f32_e32 v62, v90, v87
	v_and_b32_e32 v87, 0xffff0000, v86
	v_lshlrev_b32_e32 v86, 16, v86
	v_add_f32_e32 v89, 0, v87
	v_pk_mul_f32 v[90:91], v[86:87], v[86:87]
	v_add_f32_e32 v89, v89, v250
	v_fma_f32 v91, v250, v250, v91
	v_add_f32_e32 v89, v89, v86
	v_add_f32_e32 v118, v90, v91
	v_and_b32_e32 v91, 0xffff0000, v88
	v_lshlrev_b32_e32 v90, 16, v88
	v_add_f32_e32 v119, v89, v91
	v_pk_mul_f32 v[88:89], v[90:91], v[90:91]
	v_mul_f32_e32 v94, v65, v65
	v_add_f32_e32 v89, v89, v118
	v_add_f32_e32 v118, v119, v90
	v_add_f32_e32 v120, v88, v89
	v_and_b32_e32 v89, 0xffff0000, v60
	v_lshlrev_b32_e32 v88, 16, v60
	v_add_f32_e32 v60, v118, v89
	v_pk_mul_f32 v[118:119], v[88:89], v[88:89]
	v_pk_add_f32 v[94:95], v[94:95], v[64:65]
	v_add_f32_e32 v120, v119, v120
	v_add_f32_e32 v119, v60, v88
	v_add_f32_e32 v60, v118, v120
	ds_bpermute_b32 v120, v154, v92
	v_mul_f32_e32 v116, v63, v63
	v_pk_add_f32 v[116:117], v[116:117], v[62:63]
	v_mul_f32_e32 v118, v61, v61
	v_pk_add_f32 v[118:119], v[118:119], v[60:61]
	s_waitcnt lgkmcnt(0)
	v_pk_add_f32 v[92:93], v[92:93], v[120:121]
	ds_bpermute_b32 v121, v155, v93
	ds_bpermute_b32 v120, v155, v92
	s_add_i32 s8, s8, 4
	s_waitcnt lgkmcnt(0)
	v_pk_add_f32 v[92:93], v[92:93], v[120:121]
	ds_bpermute_b32 v121, v157, v93
	ds_bpermute_b32 v120, v157, v92
	s_waitcnt lgkmcnt(0)
	v_pk_add_f32 v[92:93], v[92:93], v[120:121]
	ds_bpermute_b32 v121, v159, v93
	ds_bpermute_b32 v120, v159, v92
	s_waitcnt lgkmcnt(0)
	v_pk_add_f32 v[92:93], v[92:93], v[120:121]
	ds_bpermute_b32 v121, v129, v93
	ds_bpermute_b32 v120, v129, v92
	s_waitcnt lgkmcnt(0)
	v_pk_add_f32 v[92:93], v[92:93], v[120:121]
	ds_bpermute_b32 v121, v131, v93
	ds_bpermute_b32 v120, v131, v92
	s_waitcnt lgkmcnt(0)
	v_pk_add_f32 v[92:93], v[92:93], v[120:121]
	ds_bpermute_b32 v121, v154, v95
	ds_bpermute_b32 v120, v154, v94
	v_pk_mul_f32 v[92:93], v[92:93], s[54:55] op_sel_hi:[1,0]
	s_waitcnt lgkmcnt(0)
	v_pk_add_f32 v[94:95], v[94:95], v[120:121]
	ds_bpermute_b32 v121, v155, v95
	ds_bpermute_b32 v120, v155, v94
	v_fma_f32 v66, -v93, v93, v92
	v_max_f32_e32 v66, 0, v66
	v_add_f32_e32 v66, 0x3727c5ac, v66
	v_rsq_f32_e32 v66, v66
	s_waitcnt lgkmcnt(0)
	v_pk_add_f32 v[94:95], v[94:95], v[120:121]
	ds_bpermute_b32 v121, v157, v95
	ds_bpermute_b32 v120, v157, v94
	v_sub_f32_e32 v69, v69, v93
	v_mul_f32_e32 v69, v69, v66
	v_fma_f32 v69, v37, v69, v138
	v_sub_f32_e32 v68, v68, v93
	s_waitcnt lgkmcnt(0)
	v_pk_add_f32 v[94:95], v[94:95], v[120:121]
	ds_bpermute_b32 v121, v159, v95
	ds_bpermute_b32 v120, v159, v94
	v_mul_f32_e32 v68, v68, v66
	v_fma_f32 v68, v141, v68, v142
	v_sub_f32_e32 v67, v67, v93
	s_waitcnt lgkmcnt(0)
	v_pk_add_f32 v[94:95], v[94:95], v[120:121]
	ds_bpermute_b32 v121, v129, v95
	ds_bpermute_b32 v120, v129, v94
	s_waitcnt lgkmcnt(0)
	v_pk_add_f32 v[94:95], v[94:95], v[120:121]
	ds_bpermute_b32 v121, v131, v95
	ds_bpermute_b32 v120, v131, v94
	s_waitcnt lgkmcnt(0)
	v_pk_add_f32 v[94:95], v[94:95], v[120:121]
	ds_bpermute_b32 v121, v154, v117
	ds_bpermute_b32 v120, v154, v116
	v_pk_mul_f32 v[94:95], v[94:95], s[54:55] op_sel_hi:[1,0]
	s_waitcnt lgkmcnt(0)
	v_pk_add_f32 v[116:117], v[116:117], v[120:121]
	ds_bpermute_b32 v121, v155, v117
	ds_bpermute_b32 v120, v155, v116
	v_fma_f32 v64, -v95, v95, v94
	v_max_f32_e32 v64, 0, v64
	v_add_f32_e32 v64, 0x3727c5ac, v64
	v_rsq_f32_e32 v64, v64
	s_waitcnt lgkmcnt(0)
	v_pk_add_f32 v[116:117], v[116:117], v[120:121]
	ds_bpermute_b32 v121, v157, v117
	ds_bpermute_b32 v120, v157, v116
	v_sub_f32_e32 v75, v75, v95
	v_mul_f32_e32 v75, v75, v64
	v_fma_f32 v75, v37, v75, v138
	v_sub_f32_e32 v65, v65, v95
	s_waitcnt lgkmcnt(0)
	v_pk_add_f32 v[116:117], v[116:117], v[120:121]
	ds_bpermute_b32 v121, v159, v117
	ds_bpermute_b32 v120, v159, v116
	s_waitcnt lgkmcnt(0)
	v_pk_add_f32 v[116:117], v[116:117], v[120:121]
	ds_bpermute_b32 v121, v129, v117
	ds_bpermute_b32 v120, v129, v116
	s_waitcnt lgkmcnt(0)
	v_pk_add_f32 v[116:117], v[116:117], v[120:121]
	ds_bpermute_b32 v121, v131, v117
	ds_bpermute_b32 v120, v131, v116
	s_waitcnt lgkmcnt(0)
	v_pk_add_f32 v[116:117], v[116:117], v[120:121]
	ds_bpermute_b32 v121, v154, v119
	ds_bpermute_b32 v120, v154, v118
	v_pk_mul_f32 v[116:117], v[116:117], s[54:55] op_sel_hi:[1,0]
	s_waitcnt lgkmcnt(0)
	v_pk_add_f32 v[118:119], v[118:119], v[120:121]
	ds_bpermute_b32 v121, v155, v119
	ds_bpermute_b32 v120, v155, v118
	v_fma_f32 v62, -v117, v117, v116
	v_max_f32_e32 v62, 0, v62
	v_add_f32_e32 v62, 0x3727c5ac, v62
	v_rsq_f32_e32 v62, v62
	s_waitcnt lgkmcnt(0)
	v_pk_add_f32 v[118:119], v[118:119], v[120:121]
	ds_bpermute_b32 v121, v157, v119
	ds_bpermute_b32 v120, v157, v118
	v_sub_f32_e32 v81, v81, v117
	v_mul_f32_e32 v81, v81, v62
	v_fma_f32 v81, v37, v81, v138
	v_sub_f32_e32 v63, v63, v117
	s_waitcnt lgkmcnt(0)
	v_pk_add_f32 v[118:119], v[118:119], v[120:121]
	ds_bpermute_b32 v121, v159, v119
	ds_bpermute_b32 v120, v159, v118
	s_waitcnt lgkmcnt(0)
	v_pk_add_f32 v[118:119], v[118:119], v[120:121]
	ds_bpermute_b32 v121, v129, v119
	ds_bpermute_b32 v120, v129, v118
	s_waitcnt lgkmcnt(0)
	v_pk_add_f32 v[118:119], v[118:119], v[120:121]
	ds_bpermute_b32 v121, v131, v119
	ds_bpermute_b32 v120, v131, v118
	s_waitcnt lgkmcnt(0)
	v_pk_add_f32 v[118:119], v[118:119], v[120:121]
	s_nop 0
	v_pk_mul_f32 v[118:119], v[118:119], s[54:55] op_sel_hi:[1,0]
	v_cvt_pk_bf16_f32 v120, v69, v75
	v_sub_f32_e32 v69, v253, v93
	v_fma_f32 v60, -v119, v119, v118
	v_max_f32_e32 v60, 0, v60
	v_add_f32_e32 v60, 0x3727c5ac, v60
	v_rsq_f32_e32 v60, v60
	v_sub_f32_e32 v87, v87, v119
	v_mul_f32_e32 v69, v69, v66
	v_add_u32_e32 v75, s9, v164
	v_mul_f32_e32 v87, v87, v60
	v_fma_f32 v87, v37, v87, v138
	v_cvt_pk_bf16_f32 v121, v81, v87
	v_sub_f32_e32 v81, v252, v95
	v_fma_f32 v69, v139, v69, v140
	v_mul_f32_e32 v81, v81, v64
	ds_write_b64 v75, v[120:121] offset:32
	v_fma_f32 v81, v139, v81, v140
	v_cvt_pk_bf16_f32 v120, v69, v81
	v_sub_f32_e32 v69, v74, v95
	v_sub_f32_e32 v87, v251, v117
	v_sub_f32_e32 v92, v250, v119
	v_mul_f32_e32 v69, v69, v64
	v_sub_f32_e32 v74, v80, v117
	v_sub_f32_e32 v80, v86, v119
	v_mul_f32_e32 v87, v87, v62
	v_mul_f32_e32 v92, v92, v60
	v_fma_f32 v69, v141, v69, v142
	v_mul_f32_e32 v74, v74, v62
	v_mul_f32_e32 v80, v80, v60
	v_fma_f32 v87, v139, v87, v140
	v_fma_f32 v92, v139, v92, v140
	v_cvt_pk_bf16_f32 v121, v87, v92
	ds_write_b64 v75, v[120:121] offset:17440
	v_fma_f32 v74, v141, v74, v142
	v_fma_f32 v80, v141, v80, v142
	v_cvt_pk_bf16_f32 v68, v68, v69
	v_cvt_pk_bf16_f32 v69, v74, v80
	ds_write_b64 v75, v[68:69] offset:34848
	v_sub_f32_e32 v68, v73, v93
	v_sub_f32_e32 v69, v79, v95
	v_mul_f32_e32 v68, v68, v66
	v_mul_f32_e32 v69, v69, v64
	v_sub_f32_e32 v73, v85, v117
	v_sub_f32_e32 v74, v91, v119
	v_fma_f32 v68, v143, v68, v144
	v_fma_f32 v69, v143, v69, v144
	v_mul_f32_e32 v73, v73, v62
	v_mul_f32_e32 v74, v74, v60
	v_fma_f32 v73, v143, v73, v144
	v_fma_f32 v74, v143, v74, v144
	v_cvt_pk_bf16_f32 v68, v68, v69
	v_cvt_pk_bf16_f32 v69, v73, v74
	ds_write_b64 v75, v[68:69] offset:52256
	v_sub_f32_e32 v68, v72, v93
	v_sub_f32_e32 v69, v78, v95
	v_sub_f32_e32 v72, v84, v117
	v_mul_f32_e32 v68, v68, v66
	v_mul_f32_e32 v69, v69, v64
	v_mul_f32_e32 v72, v72, v62
	v_sub_f32_e32 v73, v90, v119
	v_fma_f32 v68, v145, v68, v146
	v_fma_f32 v69, v145, v69, v146
	v_fma_f32 v72, v145, v72, v146
	v_mul_f32_e32 v73, v73, v60
	v_fma_f32 v73, v145, v73, v146
	v_cvt_pk_bf16_f32 v68, v68, v69
	v_cvt_pk_bf16_f32 v69, v72, v73
	v_add_u32_e32 v72, 0x11020, v75
	ds_write_b64 v72, v[68:69]
	v_sub_f32_e32 v68, v71, v93
	v_sub_f32_e32 v69, v77, v95
	v_sub_f32_e32 v71, v83, v117
	v_mul_f32_e32 v68, v68, v66
	v_mul_f32_e32 v69, v69, v64
	v_mul_f32_e32 v71, v71, v62
	v_sub_f32_e32 v72, v89, v119
	v_fma_f32 v68, v147, v68, v148
	v_fma_f32 v69, v147, v69, v148
	v_fma_f32 v71, v147, v71, v148
	v_mul_f32_e32 v72, v72, v60
	v_fma_f32 v72, v147, v72, v148
	v_cvt_pk_bf16_f32 v68, v68, v69
	v_cvt_pk_bf16_f32 v69, v71, v72
	v_add_u32_e32 v71, 0x15420, v75
	ds_write_b64 v71, v[68:69]
	v_sub_f32_e32 v68, v70, v93
	v_sub_f32_e32 v69, v76, v95
	v_sub_f32_e32 v70, v82, v117
	v_mul_f32_e32 v68, v68, v66
	v_mul_f32_e32 v69, v69, v64
	v_mul_f32_e32 v70, v70, v62
	v_sub_f32_e32 v71, v88, v119
	v_sub_f32_e32 v61, v61, v119
	v_fma_f32 v68, v149, v68, v150
	v_fma_f32 v69, v149, v69, v150
	v_fma_f32 v70, v149, v70, v150
	v_mul_f32_e32 v71, v71, v60
	v_mul_f32_e32 v62, v63, v62
	v_mul_f32_e32 v60, v61, v60
	v_fma_f32 v71, v149, v71, v150
	v_cvt_pk_bf16_f32 v68, v68, v69
	v_cvt_pk_bf16_f32 v69, v70, v71
	v_add_u32_e32 v70, 0x19820, v75
	v_mul_f32_e32 v66, v67, v66
	v_mul_f32_e32 v64, v65, v64
	v_fma_f32 v62, v151, v62, v152
	v_fma_f32 v61, v151, v60, v152
	ds_write_b64 v70, v[68:69]
	v_fma_f32 v66, v151, v66, v152
	v_fma_f32 v64, v151, v64, v152
	v_cvt_pk_bf16_f32 v60, v66, v64
	v_cvt_pk_bf16_f32 v61, v62, v61
	v_add_u32_e32 v62, 0x1dc20, v75
	s_add_i32 s9, s9, 8
	ds_write_b64 v62, v[60:61]
	s_waitcnt vmcnt(1)
	v_perm_b32 v60, v248, v249, s67
	v_perm_b32 v88, v246, v247, s67
	v_perm_b32 v86, v244, v245, s67
	v_perm_b32 v62, v242, v243, s67
	v_perm_b32 v82, v240, v241, s67
	v_perm_b32 v80, v238, v239, s67
	v_perm_b32 v64, v236, v237, s67
	v_perm_b32 v76, v234, v235, s67
	v_perm_b32 v74, v232, v233, s67
	v_perm_b32 v66, v229, v230, s67
	v_perm_b32 v70, v227, v228, s67
	v_perm_b32 v68, v225, v226, s67
	s_cmp_eq_u32 s9, 0
	s_cbranch_scc0 .LBB0_417
	s_add_u32 s8, s16, 0x100
	s_addc_u32 s9, s17, 0
	v_or_b32_e32 v38, s8, v98
	s_add_u32 s8, s16, 0x180
	v_mov_b32_e32 v39, s9
	s_addc_u32 s9, s17, 0
	v_mov_b32_e32 v61, s9
	v_or_b32_e32 v60, s8, v98
	v_lshlrev_b64 v[38:39], 8, v[38:39]
	v_lshlrev_b64 v[60:61], 8, v[60:61]
	v_lshl_add_u64 v[38:39], s[12:13], 0, v[38:39]
	v_lshlrev_b32_e32 v164, 1, v36
	v_mov_b32_e32 v165, v2
	v_lshl_add_u64 v[60:61], s[12:13], 0, v[60:61]
	v_add_u32_e32 v66, 0, v40
	v_lshl_add_u64 v[36:37], v[38:39], 0, v[164:165]
	v_lshl_add_u64 v[60:61], v[60:61], 0, v[164:165]
	v_mad_u32_u24 v67, v98, s96, v66
	global_load_dwordx4 v[92:95], v[36:37], off
	global_load_dwordx4 v[88:91], v[36:37], off offset:64
	global_load_dwordx4 v[84:87], v[36:37], off offset:128
	s_nop 0
	global_load_dwordx4 v[36:39], v[36:37], off offset:192
	s_nop 0
	global_load_dwordx4 v[80:83], v[60:61], off
	global_load_dwordx4 v[76:79], v[60:61], off offset:64
	global_load_dwordx4 v[72:75], v[60:61], off offset:128
	global_load_dwordx4 v[68:71], v[60:61], off offset:192
	global_load_dwordx2 v[162:163], v[58:59], off offset:2048 nt
	global_load_dwordx2 v[160:161], v[58:59], off offset:2080 nt
	global_load_dwordx2 v[158:159], v[58:59], off offset:2112 nt
	global_load_dwordx2 v[156:157], v[58:59], off offset:2144 nt
	global_load_dwordx2 v[154:155], v[58:59], off offset:2176 nt
	global_load_dwordx2 v[152:153], v[58:59], off offset:2208 nt
	global_load_dwordx2 v[150:151], v[58:59], off offset:2240 nt
	global_load_dwordx2 v[148:149], v[58:59], off offset:2272 nt
	global_load_dwordx2 v[146:147], v[58:59], off offset:2304 nt
	global_load_dwordx2 v[144:145], v[58:59], off offset:2336 nt
	global_load_dwordx2 v[142:143], v[58:59], off offset:2368 nt
	global_load_dwordx2 v[140:141], v[58:59], off offset:2400 nt
	global_load_dwordx2 v[138:139], v[58:59], off offset:2432 nt
	global_load_dwordx2 v[120:121], v[58:59], off offset:2464 nt
	global_load_dwordx2 v[118:119], v[58:59], off offset:2496 nt
	global_load_dwordx2 v[116:117], v[58:59], off offset:2528 nt
	s_waitcnt lgkmcnt(0)
	s_barrier
	ds_read_b128 v[58:61], v67
	ds_read_b128 v[62:65], v67 offset:64
	s_waitcnt lgkmcnt(1)
	v_mfma_f32_16x16x32_bf16 v[58:61], v[58:61], v[32:35], 0
	s_add_u32 s8, s16, 0x200
	s_addc_u32 s9, s17, 0
	v_mul_u32_u24_e32 v233, 0x110, v98
	s_waitcnt lgkmcnt(0)
	v_mfma_f32_16x16x32_bf16 v[58:61], v[62:65], v[28:31], v[58:61]
	ds_read_b128 v[62:65], v67 offset:128
	v_add3_u32 v241, 0, v233, v40
	v_fmamk_f32 v3, v3, 0x3b000000, v221
	s_waitcnt lgkmcnt(0)
	v_mfma_f32_16x16x32_bf16 v[58:61], v[62:65], v[24:27], v[58:61]
	ds_read_b128 v[62:65], v67 offset:192
	v_cmp_gt_u32_e32 vcc, 16, v97
	s_waitcnt lgkmcnt(0)
	v_mfma_f32_16x16x32_bf16 v[58:61], v[62:65], v[20:23], v[58:61]
	v_lshlrev_b32_e32 v62, 16, v56
	v_and_b32_e32 v56, 0xffff0000, v56
	s_nop 5
	v_add_f32_e32 v59, v231, v59
	v_mul_f32_e32 v56, v59, v56
	v_lshlrev_b32_e32 v59, 16, v57
	v_add_f32_e32 v60, v231, v60
	v_mul_f32_e32 v59, v60, v59
	v_and_b32_e32 v57, 0xffff0000, v57
	v_add_f32_e32 v60, v231, v61
	v_add_f32_e32 v58, v231, v58
	v_mul_f32_e32 v57, v60, v57
	v_mul_f32_e32 v58, v58, v62
	v_mul_f32_e32 v60, v56, v56
	v_mul_f32_e32 v61, v57, v57
	v_fmac_f32_e32 v60, v58, v58
	v_fmac_f32_e32 v61, v59, v59
	v_cvt_pk_bf16_f32 v226, v58, v56
	v_cvt_pk_bf16_f32 v225, v59, v57
	ds_read_b128 v[56:59], v67 offset:4352
	v_add_f32_e32 v64, v60, v61
	ds_read_b128 v[60:63], v67 offset:4416
	s_waitcnt lgkmcnt(1)
	v_mfma_f32_16x16x32_bf16 v[56:59], v[56:59], v[32:35], 0
	s_waitcnt lgkmcnt(0)
	v_mfma_f32_16x16x32_bf16 v[56:59], v[60:63], v[28:31], v[56:59]
	ds_read_b128 v[60:63], v67 offset:4480
	s_waitcnt lgkmcnt(0)
	v_mfma_f32_16x16x32_bf16 v[56:59], v[60:63], v[24:27], v[56:59]
	ds_read_b128 v[60:63], v67 offset:4544
	s_waitcnt lgkmcnt(0)
	v_mfma_f32_16x16x32_bf16 v[56:59], v[60:63], v[20:23], v[56:59]
	v_lshlrev_b32_e32 v60, 16, v54
	v_and_b32_e32 v54, 0xffff0000, v54
	s_nop 5
	v_add_f32_e32 v57, v231, v57
	v_mul_f32_e32 v54, v57, v54
	v_lshlrev_b32_e32 v57, 16, v55
	v_add_f32_e32 v58, v231, v58
	v_mul_f32_e32 v57, v58, v57
	v_and_b32_e32 v55, 0xffff0000, v55
	v_add_f32_e32 v58, v231, v59
	v_add_f32_e32 v56, v231, v56
	v_mul_f32_e32 v55, v58, v55
	v_mul_f32_e32 v56, v56, v60
	v_mul_f32_e32 v58, v54, v54
	v_mul_f32_e32 v59, v55, v55
	v_fmac_f32_e32 v58, v56, v56
	v_fmac_f32_e32 v59, v57, v57
	v_cvt_pk_bf16_f32 v228, v56, v54
	v_cvt_pk_bf16_f32 v227, v57, v55
	ds_read_b128 v[54:57], v67 offset:8704
	v_add_f32_e32 v58, v58, v59
	v_add_f32_e32 v62, v64, v58
	ds_read_b128 v[58:61], v67 offset:8768
	s_waitcnt lgkmcnt(1)
	v_mfma_f32_16x16x32_bf16 v[54:57], v[54:57], v[32:35], 0
	s_waitcnt lgkmcnt(0)
	v_mfma_f32_16x16x32_bf16 v[54:57], v[58:61], v[28:31], v[54:57]
	ds_read_b128 v[58:61], v67 offset:8832
	s_waitcnt lgkmcnt(0)
	v_mfma_f32_16x16x32_bf16 v[54:57], v[58:61], v[24:27], v[54:57]
	ds_read_b128 v[58:61], v67 offset:8896
	s_waitcnt lgkmcnt(0)
	v_mfma_f32_16x16x32_bf16 v[54:57], v[58:61], v[20:23], v[54:57]
	v_lshlrev_b32_e32 v58, 16, v52
	v_and_b32_e32 v52, 0xffff0000, v52
	s_nop 5
	v_add_f32_e32 v55, v231, v55
	v_mul_f32_e32 v52, v55, v52
	v_lshlrev_b32_e32 v55, 16, v53
	v_add_f32_e32 v56, v231, v56
	v_mul_f32_e32 v55, v56, v55
	v_and_b32_e32 v53, 0xffff0000, v53
	v_add_f32_e32 v56, v231, v57
	v_add_f32_e32 v54, v231, v54
	v_mul_f32_e32 v53, v56, v53
	v_mul_f32_e32 v54, v54, v58
	v_mul_f32_e32 v56, v52, v52
	v_mul_f32_e32 v57, v53, v53
	v_fmac_f32_e32 v56, v54, v54
	v_fmac_f32_e32 v57, v55, v55
	v_add_f32_e32 v56, v56, v57
	v_cvt_pk_bf16_f32 v230, v54, v52
	v_or_b32_e32 v52, 48, v97
	v_add_f32_e32 v234, v62, v56
	v_mad_u32_u24 v56, v52, s96, v66
	v_cvt_pk_bf16_f32 v229, v55, v53
	v_mul_u32_u24_e32 v239, 0x110, v52
	ds_read_b128 v[52:55], v56
	s_waitcnt lgkmcnt(0)
	v_mfma_f32_16x16x32_bf16 v[32:35], v[52:55], v[32:35], 0
	ds_read_b128 v[52:55], v56 offset:64
	v_add3_u32 v242, 0, v239, v40
	s_waitcnt lgkmcnt(0)
	v_mfma_f32_16x16x32_bf16 v[28:31], v[52:55], v[28:31], v[32:35]
	s_nop 3
	ds_read_b128 v[32:35], v56 offset:128
	s_waitcnt lgkmcnt(0)
	v_mfma_f32_16x16x32_bf16 v[24:27], v[32:35], v[24:27], v[28:31]
	s_nop 2
	ds_read_b128 v[28:31], v56 offset:192
	s_waitcnt lgkmcnt(0)
	v_mfma_f32_16x16x32_bf16 v[20:23], v[28:31], v[20:23], v[24:27]
	s_nop 2
	v_lshlrev_b32_e32 v24, 16, v50
	s_nop 3
	v_add_f32_e32 v20, v231, v20
	v_mul_f32_e32 v20, v20, v24
	v_and_b32_e32 v24, 0xffff0000, v50
	v_add_f32_e32 v21, v231, v21
	v_mul_f32_e32 v21, v21, v24
	v_lshlrev_b32_e32 v24, 16, v51
	v_add_f32_e32 v22, v231, v22
	v_mul_f32_e32 v22, v22, v24
	v_and_b32_e32 v24, 0xffff0000, v51
	v_add_f32_e32 v23, v231, v23
	v_mul_f32_e32 v23, v23, v24
	v_mul_f32_e32 v24, v21, v21
	v_fmac_f32_e32 v24, v20, v20
	v_cvt_pk_bf16_f32 v232, v20, v21
	v_mov_b32_e32 v21, s9
	v_or_b32_e32 v20, s8, v98
	v_lshlrev_b64 v[20:21], 8, v[20:21]
	v_lshl_add_u64 v[20:21], s[12:13], 0, v[20:21]
	v_mul_f32_e32 v25, v23, v23
	v_lshl_add_u64 v[20:21], v[20:21], 0, v[164:165]
	v_fmac_f32_e32 v25, v22, v22
	v_cvt_pk_bf16_f32 v231, v22, v23
	global_load_dwordx4 v[64:67], v[20:21], off
	global_load_dwordx4 v[60:63], v[20:21], off offset:64
	global_load_dwordx4 v[56:59], v[20:21], off offset:128
	global_load_dwordx4 v[52:55], v[20:21], off offset:192
	ds_read_b128 v[20:23], v241 offset:17408
	v_add_f32_e32 v24, v24, v25
	v_add_f32_e32 v28, v234, v24
	ds_read_b128 v[24:27], v241 offset:17472
	s_waitcnt lgkmcnt(1)
	v_mfma_f32_16x16x32_bf16 v[20:23], v[20:23], v[16:19], 0
	s_add_u32 s8, s16, 0x280
	s_addc_u32 s9, s17, 0
	s_waitcnt lgkmcnt(0)
	v_mfma_f32_16x16x32_bf16 v[20:23], v[24:27], v[12:15], v[20:23]
	ds_read_b128 v[24:27], v241 offset:17536
	s_waitcnt lgkmcnt(0)
	v_mfma_f32_16x16x32_bf16 v[20:23], v[24:27], v[8:11], v[20:23]
	ds_read_b128 v[24:27], v241 offset:17600
	s_waitcnt lgkmcnt(0)
	v_mfma_f32_16x16x32_bf16 v[20:23], v[24:27], v[4:7], v[20:23]
	v_lshlrev_b32_e32 v24, 16, v48
	s_nop 6
	v_add_f32_e32 v20, v41, v20
	v_mul_f32_e32 v20, v20, v24
	v_and_b32_e32 v24, 0xffff0000, v48
	v_add_f32_e32 v21, v41, v21
	v_mul_f32_e32 v21, v21, v24
	v_lshlrev_b32_e32 v24, 16, v49
	v_add_f32_e32 v22, v41, v22
	v_mul_f32_e32 v22, v22, v24
	v_and_b32_e32 v24, 0xffff0000, v49
	v_add_f32_e32 v23, v41, v23
	v_mul_f32_e32 v23, v23, v24
	v_mul_f32_e32 v24, v21, v21
	v_mul_f32_e32 v25, v23, v23
	v_fmac_f32_e32 v24, v20, v20
	v_fmac_f32_e32 v25, v22, v22
	v_cvt_pk_bf16_f32 v234, v20, v21
	v_cvt_pk_bf16_f32 v233, v22, v23
	ds_read_b128 v[20:23], v241 offset:21760
	v_add_f32_e32 v24, v24, v25
	v_add_f32_e32 v28, v28, v24
	ds_read_b128 v[24:27], v241 offset:21824
	s_waitcnt lgkmcnt(1)
	v_mfma_f32_16x16x32_bf16 v[20:23], v[20:23], v[16:19], 0
	s_waitcnt lgkmcnt(0)
	v_mfma_f32_16x16x32_bf16 v[20:23], v[24:27], v[12:15], v[20:23]
	ds_read_b128 v[24:27], v241 offset:21888
	s_waitcnt lgkmcnt(0)
	v_mfma_f32_16x16x32_bf16 v[20:23], v[24:27], v[8:11], v[20:23]
	ds_read_b128 v[24:27], v241 offset:21952
	s_waitcnt lgkmcnt(0)
	v_mfma_f32_16x16x32_bf16 v[20:23], v[24:27], v[4:7], v[20:23]
	v_lshlrev_b32_e32 v24, 16, v46
	s_nop 6
	v_add_f32_e32 v20, v41, v20
	v_mul_f32_e32 v20, v20, v24
	v_and_b32_e32 v24, 0xffff0000, v46
	v_add_f32_e32 v21, v41, v21
	v_mul_f32_e32 v21, v21, v24
	v_lshlrev_b32_e32 v24, 16, v47
	v_add_f32_e32 v22, v41, v22
	v_mul_f32_e32 v22, v22, v24
	v_and_b32_e32 v24, 0xffff0000, v47
	v_add_f32_e32 v23, v41, v23
	v_mul_f32_e32 v23, v23, v24
	v_mul_f32_e32 v24, v21, v21
	v_mul_f32_e32 v25, v23, v23
	v_fmac_f32_e32 v24, v20, v20
	v_fmac_f32_e32 v25, v22, v22
	v_cvt_pk_bf16_f32 v236, v20, v21
	v_cvt_pk_bf16_f32 v235, v22, v23
	ds_read_b128 v[20:23], v241 offset:26112
	v_add_f32_e32 v24, v24, v25
	v_add_f32_e32 v28, v28, v24
	ds_read_b128 v[24:27], v241 offset:26176
	s_waitcnt lgkmcnt(1)
	v_mfma_f32_16x16x32_bf16 v[20:23], v[20:23], v[16:19], 0
	s_waitcnt lgkmcnt(0)
	v_mfma_f32_16x16x32_bf16 v[20:23], v[24:27], v[12:15], v[20:23]
	ds_read_b128 v[24:27], v241 offset:26240
	s_waitcnt lgkmcnt(0)
	v_mfma_f32_16x16x32_bf16 v[20:23], v[24:27], v[8:11], v[20:23]
	ds_read_b128 v[24:27], v241 offset:26304
	s_waitcnt lgkmcnt(0)
	v_mfma_f32_16x16x32_bf16 v[20:23], v[24:27], v[4:7], v[20:23]
	v_lshlrev_b32_e32 v24, 16, v44
	s_nop 6
	v_add_f32_e32 v20, v41, v20
	v_mul_f32_e32 v20, v20, v24
	v_and_b32_e32 v24, 0xffff0000, v44
	v_add_f32_e32 v21, v41, v21
	v_mul_f32_e32 v21, v21, v24
	v_lshlrev_b32_e32 v24, 16, v45
	v_add_f32_e32 v22, v41, v22
	v_mul_f32_e32 v22, v22, v24
	v_and_b32_e32 v24, 0xffff0000, v45
	v_add_f32_e32 v23, v41, v23
	v_mul_f32_e32 v23, v23, v24
	v_mul_f32_e32 v24, v21, v21
	v_mul_f32_e32 v25, v23, v23
	v_fmac_f32_e32 v24, v20, v20
	v_fmac_f32_e32 v25, v22, v22
	v_cvt_pk_bf16_f32 v238, v20, v21
	v_cvt_pk_bf16_f32 v237, v22, v23
	ds_read_b128 v[20:23], v242 offset:17408
	s_waitcnt lgkmcnt(0)
	v_mfma_f32_16x16x32_bf16 v[16:19], v[20:23], v[16:19], 0
	ds_read_b128 v[20:23], v242 offset:17472
	v_add_f32_e32 v24, v24, v25
	v_add_f32_e32 v24, v28, v24
	s_waitcnt lgkmcnt(0)
	v_mfma_f32_16x16x32_bf16 v[12:15], v[20:23], v[12:15], v[16:19]
	s_nop 2
	ds_read_b128 v[16:19], v242 offset:17536
	s_waitcnt lgkmcnt(0)
	v_mfma_f32_16x16x32_bf16 v[8:11], v[16:19], v[8:11], v[12:15]
	s_nop 2
	ds_read_b128 v[12:15], v242 offset:17600
	s_waitcnt lgkmcnt(0)
	v_mfma_f32_16x16x32_bf16 v[4:7], v[12:15], v[4:7], v[8:11]
	s_nop 2
	v_lshlrev_b32_e32 v8, 16, v42
	s_nop 3
	v_add_f32_e32 v4, v41, v4
	v_mul_f32_e32 v4, v4, v8
	v_and_b32_e32 v8, 0xffff0000, v42
	v_add_f32_e32 v5, v41, v5
	v_mul_f32_e32 v5, v5, v8
	v_lshlrev_b32_e32 v8, 16, v43
	v_add_f32_e32 v6, v41, v6
	v_mul_f32_e32 v6, v6, v8
	v_and_b32_e32 v8, 0xffff0000, v43
	v_add_f32_e32 v7, v41, v7
	v_mul_f32_e32 v7, v7, v8
	v_mul_f32_e32 v8, v5, v5
	v_fmac_f32_e32 v8, v4, v4
	v_cvt_pk_bf16_f32 v240, v4, v5
	v_mov_b32_e32 v5, s9
	v_or_b32_e32 v4, s8, v98
	v_lshlrev_b64 v[4:5], 8, v[4:5]
	v_lshl_add_u64 v[4:5], s[12:13], 0, v[4:5]
	v_mul_f32_e32 v9, v7, v7
	v_lshl_add_u64 v[4:5], v[4:5], 0, v[164:165]
	v_fmac_f32_e32 v9, v6, v6
	v_cvt_pk_bf16_f32 v239, v6, v7
	global_load_dwordx4 v[48:51], v[4:5], off
	global_load_dwordx4 v[44:47], v[4:5], off offset:64
	global_load_dwordx4 v[40:43], v[4:5], off offset:128
	global_load_dwordx4 v[32:35], v[4:5], off offset:192
	ds_read_b128 v[4:7], v241 offset:34816
	v_add_f32_e32 v8, v8, v9
	v_add_f32_e32 v12, v24, v8
	ds_read_b128 v[8:11], v241 offset:34880
	s_waitcnt vmcnt(31) lgkmcnt(1)
	v_mfma_f32_16x16x32_bf16 v[4:7], v[4:7], v[92:95], 0
	s_add_u32 s8, s16, 0x300
	s_addc_u32 s9, s17, 0
	s_waitcnt vmcnt(30) lgkmcnt(0)
	v_mfma_f32_16x16x32_bf16 v[4:7], v[8:11], v[88:91], v[4:7]
	ds_read_b128 v[8:11], v241 offset:34944
	s_waitcnt vmcnt(29) lgkmcnt(0)
	v_mfma_f32_16x16x32_bf16 v[4:7], v[8:11], v[84:87], v[4:7]
	ds_read_b128 v[8:11], v241 offset:35008
	s_waitcnt vmcnt(28) lgkmcnt(0)
	v_mfma_f32_16x16x32_bf16 v[4:7], v[8:11], v[36:39], v[4:7]
	v_lshlrev_b32_e32 v8, 16, v114
	s_nop 6
	v_add_f32_e32 v4, v167, v4
	v_mul_f32_e32 v4, v4, v8
	v_and_b32_e32 v8, 0xffff0000, v114
	v_add_f32_e32 v5, v167, v5
	v_mul_f32_e32 v5, v5, v8
	v_lshlrev_b32_e32 v8, 16, v115
	v_add_f32_e32 v6, v167, v6
	v_mul_f32_e32 v6, v6, v8
	v_and_b32_e32 v8, 0xffff0000, v115
	v_add_f32_e32 v7, v167, v7
	v_mul_f32_e32 v7, v7, v8
	v_mul_f32_e32 v8, v5, v5
	v_mul_f32_e32 v9, v7, v7
	v_fmac_f32_e32 v8, v4, v4
	v_fmac_f32_e32 v9, v6, v6
	v_cvt_pk_bf16_f32 v115, v4, v5
	v_cvt_pk_bf16_f32 v114, v6, v7
	ds_read_b128 v[4:7], v241 offset:39168
	v_add_f32_e32 v8, v8, v9
	v_add_f32_e32 v12, v12, v8
	ds_read_b128 v[8:11], v241 offset:39232
	s_waitcnt lgkmcnt(1)
	v_mfma_f32_16x16x32_bf16 v[4:7], v[4:7], v[92:95], 0
	s_waitcnt lgkmcnt(0)
	v_mfma_f32_16x16x32_bf16 v[4:7], v[8:11], v[88:91], v[4:7]
	ds_read_b128 v[8:11], v241 offset:39296
	s_waitcnt lgkmcnt(0)
	v_mfma_f32_16x16x32_bf16 v[4:7], v[8:11], v[84:87], v[4:7]
	ds_read_b128 v[8:11], v241 offset:39360
	s_waitcnt lgkmcnt(0)
	v_mfma_f32_16x16x32_bf16 v[4:7], v[8:11], v[36:39], v[4:7]
	v_lshlrev_b32_e32 v8, 16, v112
	s_nop 6
	v_add_f32_e32 v4, v167, v4
	v_mul_f32_e32 v4, v4, v8
	v_and_b32_e32 v8, 0xffff0000, v112
	v_add_f32_e32 v5, v167, v5
	v_mul_f32_e32 v5, v5, v8
	v_lshlrev_b32_e32 v8, 16, v113
	v_add_f32_e32 v6, v167, v6
	v_mul_f32_e32 v6, v6, v8
	v_and_b32_e32 v8, 0xffff0000, v113
	v_add_f32_e32 v7, v167, v7
	v_mul_f32_e32 v7, v7, v8
	v_mul_f32_e32 v8, v5, v5
	v_mul_f32_e32 v9, v7, v7
	v_fmac_f32_e32 v8, v4, v4
	v_fmac_f32_e32 v9, v6, v6
	v_cvt_pk_bf16_f32 v113, v4, v5
	v_cvt_pk_bf16_f32 v112, v6, v7
	ds_read_b128 v[4:7], v241 offset:43520
	v_add_f32_e32 v8, v8, v9
	v_add_f32_e32 v12, v12, v8
	ds_read_b128 v[8:11], v241 offset:43584
	s_waitcnt lgkmcnt(1)
	v_mfma_f32_16x16x32_bf16 v[4:7], v[4:7], v[92:95], 0
	s_waitcnt lgkmcnt(0)
	v_mfma_f32_16x16x32_bf16 v[4:7], v[8:11], v[88:91], v[4:7]
	ds_read_b128 v[8:11], v241 offset:43648
	s_waitcnt lgkmcnt(0)
	v_mfma_f32_16x16x32_bf16 v[4:7], v[8:11], v[84:87], v[4:7]
	ds_read_b128 v[8:11], v241 offset:43712
	s_waitcnt lgkmcnt(0)
	v_mfma_f32_16x16x32_bf16 v[4:7], v[8:11], v[36:39], v[4:7]
	v_lshlrev_b32_e32 v8, 16, v110
	s_nop 6
	v_add_f32_e32 v4, v167, v4
	v_mul_f32_e32 v4, v4, v8
	v_and_b32_e32 v8, 0xffff0000, v110
	v_add_f32_e32 v5, v167, v5
	v_mul_f32_e32 v5, v5, v8
	v_lshlrev_b32_e32 v8, 16, v111
	v_add_f32_e32 v6, v167, v6
	v_mul_f32_e32 v6, v6, v8
	v_and_b32_e32 v8, 0xffff0000, v111
	v_add_f32_e32 v7, v167, v7
	v_mul_f32_e32 v7, v7, v8
	v_mul_f32_e32 v8, v5, v5
	v_mul_f32_e32 v9, v7, v7
	v_fmac_f32_e32 v8, v4, v4
	v_fmac_f32_e32 v9, v6, v6
	v_cvt_pk_bf16_f32 v111, v4, v5
	v_cvt_pk_bf16_f32 v110, v6, v7
	ds_read_b128 v[4:7], v242 offset:34816
	v_add_f32_e32 v8, v8, v9
	v_add_f32_e32 v12, v12, v8
	ds_read_b128 v[8:11], v242 offset:34880
	s_waitcnt lgkmcnt(1)
	v_mfma_f32_16x16x32_bf16 v[4:7], v[4:7], v[92:95], 0
	s_waitcnt lgkmcnt(0)
	v_mfma_f32_16x16x32_bf16 v[4:7], v[8:11], v[88:91], v[4:7]
	ds_read_b128 v[8:11], v242 offset:34944
	s_waitcnt lgkmcnt(0)
	v_mfma_f32_16x16x32_bf16 v[4:7], v[8:11], v[84:87], v[4:7]
	ds_read_b128 v[8:11], v242 offset:35008
	s_waitcnt lgkmcnt(0)
	v_mfma_f32_16x16x32_bf16 v[4:7], v[8:11], v[36:39], v[4:7]
	v_lshlrev_b32_e32 v8, 16, v108
	s_nop 6
	v_add_f32_e32 v4, v167, v4
	v_mul_f32_e32 v4, v4, v8
	v_and_b32_e32 v8, 0xffff0000, v108
	v_add_f32_e32 v5, v167, v5
	v_mul_f32_e32 v5, v5, v8
	v_lshlrev_b32_e32 v8, 16, v109
	v_add_f32_e32 v6, v167, v6
	v_mul_f32_e32 v6, v6, v8
	v_and_b32_e32 v8, 0xffff0000, v109
	v_add_f32_e32 v7, v167, v7
	v_mul_f32_e32 v7, v7, v8
	v_mul_f32_e32 v8, v5, v5
	v_fmac_f32_e32 v8, v4, v4
	v_cvt_pk_bf16_f32 v85, v4, v5
	v_mov_b32_e32 v5, s9
	v_or_b32_e32 v4, s8, v98
	v_lshlrev_b64 v[4:5], 8, v[4:5]
	v_mul_f32_e32 v9, v7, v7
	v_lshl_add_u64 v[4:5], s[12:13], 0, v[4:5]
	v_fmac_f32_e32 v9, v6, v6
	v_lshl_add_u64 v[4:5], v[4:5], 0, v[164:165]
	v_add_f32_e32 v13, v8, v9
	v_cvt_pk_bf16_f32 v84, v6, v7
	global_load_dwordx4 v[36:39], v[4:5], off
	global_load_dwordx4 v[24:27], v[4:5], off offset:64
	global_load_dwordx4 v[16:19], v[4:5], off offset:128
	global_load_dwordx4 v[8:11], v[4:5], off offset:192
	ds_read_b128 v[4:7], v241 offset:52224
	v_add_f32_e32 v20, v12, v13
	ds_read_b128 v[12:15], v241 offset:52288
	s_waitcnt vmcnt(31) lgkmcnt(1)
	v_mfma_f32_16x16x32_bf16 v[4:7], v[4:7], v[80:83], 0
	s_add_u32 s8, s16, 0x380
	s_addc_u32 s9, s17, 0
	s_waitcnt vmcnt(30) lgkmcnt(0)
	v_mfma_f32_16x16x32_bf16 v[4:7], v[12:15], v[76:79], v[4:7]
	ds_read_b128 v[12:15], v241 offset:52352
	s_waitcnt vmcnt(29) lgkmcnt(0)
	v_mfma_f32_16x16x32_bf16 v[4:7], v[12:15], v[72:75], v[4:7]
	ds_read_b128 v[12:15], v241 offset:52416
	s_waitcnt vmcnt(28) lgkmcnt(0)
	v_mfma_f32_16x16x32_bf16 v[4:7], v[12:15], v[68:71], v[4:7]
	v_lshlrev_b32_e32 v12, 16, v106
	s_nop 6
	v_add_f32_e32 v4, v166, v4
	v_mul_f32_e32 v4, v4, v12
	v_and_b32_e32 v12, 0xffff0000, v106
	v_add_f32_e32 v5, v166, v5
	v_mul_f32_e32 v5, v5, v12
	v_lshlrev_b32_e32 v12, 16, v107
	v_add_f32_e32 v6, v166, v6
	v_mul_f32_e32 v6, v6, v12
	v_and_b32_e32 v12, 0xffff0000, v107
	v_add_f32_e32 v7, v166, v7
	v_mul_f32_e32 v7, v7, v12
	v_mul_f32_e32 v12, v5, v5
	v_mul_f32_e32 v13, v7, v7
	v_fmac_f32_e32 v12, v4, v4
	v_fmac_f32_e32 v13, v6, v6
	v_cvt_pk_bf16_f32 v87, v4, v5
	v_cvt_pk_bf16_f32 v86, v6, v7
	ds_read_b128 v[4:7], v241 offset:56576
	v_add_f32_e32 v12, v12, v13
	v_add_f32_e32 v20, v20, v12
	ds_read_b128 v[12:15], v241 offset:56640
	s_waitcnt lgkmcnt(1)
	v_mfma_f32_16x16x32_bf16 v[4:7], v[4:7], v[80:83], 0
	s_waitcnt lgkmcnt(0)
	v_mfma_f32_16x16x32_bf16 v[4:7], v[12:15], v[76:79], v[4:7]
	ds_read_b128 v[12:15], v241 offset:56704
	s_waitcnt lgkmcnt(0)
	v_mfma_f32_16x16x32_bf16 v[4:7], v[12:15], v[72:75], v[4:7]
	ds_read_b128 v[12:15], v241 offset:56768
	s_waitcnt lgkmcnt(0)
	v_mfma_f32_16x16x32_bf16 v[4:7], v[12:15], v[68:71], v[4:7]
	v_lshlrev_b32_e32 v12, 16, v104
	s_nop 6
	v_add_f32_e32 v4, v166, v4
	v_mul_f32_e32 v4, v4, v12
	v_and_b32_e32 v12, 0xffff0000, v104
	v_add_f32_e32 v5, v166, v5
	v_mul_f32_e32 v5, v5, v12
	v_lshlrev_b32_e32 v12, 16, v105
	v_add_f32_e32 v6, v166, v6
	v_mul_f32_e32 v6, v6, v12
	v_and_b32_e32 v12, 0xffff0000, v105
	v_add_f32_e32 v7, v166, v7
	v_mul_f32_e32 v7, v7, v12
	v_mul_f32_e32 v12, v5, v5
	v_mul_f32_e32 v13, v7, v7
	v_fmac_f32_e32 v12, v4, v4
	v_fmac_f32_e32 v13, v6, v6
	v_cvt_pk_bf16_f32 v89, v4, v5
	v_cvt_pk_bf16_f32 v88, v6, v7
	ds_read_b128 v[4:7], v241 offset:60928
	v_add_f32_e32 v12, v12, v13
	v_add_f32_e32 v20, v20, v12
	ds_read_b128 v[12:15], v241 offset:60992
	s_waitcnt lgkmcnt(1)
	v_mfma_f32_16x16x32_bf16 v[4:7], v[4:7], v[80:83], 0
	s_waitcnt lgkmcnt(0)
	v_mfma_f32_16x16x32_bf16 v[4:7], v[12:15], v[76:79], v[4:7]
	ds_read_b128 v[12:15], v241 offset:61056
	s_waitcnt lgkmcnt(0)
	v_mfma_f32_16x16x32_bf16 v[4:7], v[12:15], v[72:75], v[4:7]
	ds_read_b128 v[12:15], v241 offset:61120
	s_waitcnt lgkmcnt(0)
	v_mfma_f32_16x16x32_bf16 v[4:7], v[12:15], v[68:71], v[4:7]
	v_lshlrev_b32_e32 v12, 16, v102
	s_nop 6
	v_add_f32_e32 v4, v166, v4
	v_mul_f32_e32 v4, v4, v12
	v_and_b32_e32 v12, 0xffff0000, v102
	v_add_f32_e32 v5, v166, v5
	v_mul_f32_e32 v5, v5, v12
	v_lshlrev_b32_e32 v12, 16, v103
	v_add_f32_e32 v6, v166, v6
	v_mul_f32_e32 v6, v6, v12
	v_and_b32_e32 v12, 0xffff0000, v103
	v_add_f32_e32 v7, v166, v7
	v_mul_f32_e32 v7, v7, v12
	v_mul_f32_e32 v12, v5, v5
	v_mul_f32_e32 v13, v7, v7
	v_fmac_f32_e32 v12, v4, v4
	v_fmac_f32_e32 v13, v6, v6
	v_cvt_pk_bf16_f32 v91, v4, v5
	v_cvt_pk_bf16_f32 v90, v6, v7
	ds_read_b128 v[4:7], v242 offset:52224
	v_add_f32_e32 v12, v12, v13
	v_add_f32_e32 v92, v20, v12
	ds_read_b128 v[12:15], v242 offset:52288
	s_waitcnt lgkmcnt(1)
	v_mfma_f32_16x16x32_bf16 v[4:7], v[4:7], v[80:83], 0
	v_add_u32_e32 v81, 0x12100, v241
	v_add_u32_e32 v83, 0x13200, v241
	s_waitcnt lgkmcnt(0)
	v_mfma_f32_16x16x32_bf16 v[4:7], v[12:15], v[76:79], v[4:7]
	ds_read_b128 v[12:15], v242 offset:52352
	v_add_u32_e32 v79, 0x11000, v241
	s_waitcnt lgkmcnt(0)
	v_mfma_f32_16x16x32_bf16 v[4:7], v[12:15], v[72:75], v[4:7]
	ds_read_b128 v[12:15], v242 offset:52416
	s_waitcnt lgkmcnt(0)
	v_mfma_f32_16x16x32_bf16 v[4:7], v[12:15], v[68:71], v[4:7]
	v_lshlrev_b32_e32 v12, 16, v100
	s_nop 6
	v_add_f32_e32 v4, v166, v4
	v_mul_f32_e32 v4, v4, v12
	v_and_b32_e32 v12, 0xffff0000, v100
	v_add_f32_e32 v5, v166, v5
	v_mul_f32_e32 v5, v5, v12
	v_lshlrev_b32_e32 v12, 16, v101
	v_add_f32_e32 v6, v166, v6
	v_mul_f32_e32 v6, v6, v12
	v_and_b32_e32 v12, 0xffff0000, v101
	v_add_f32_e32 v7, v166, v7
	v_mul_f32_e32 v7, v7, v12
	v_mul_f32_e32 v12, v5, v5
	v_fmac_f32_e32 v12, v4, v4
	v_cvt_pk_bf16_f32 v69, v4, v5
	v_mov_b32_e32 v5, s9
	v_or_b32_e32 v4, s8, v98
	v_mul_f32_e32 v13, v7, v7
	v_lshlrev_b64 v[4:5], 8, v[4:5]
	v_fmac_f32_e32 v13, v6, v6
	v_lshl_add_u64 v[4:5], s[12:13], 0, v[4:5]
	v_add_f32_e32 v70, v12, v13
	v_lshl_add_u64 v[4:5], v[4:5], 0, v[164:165]
	v_cvt_pk_bf16_f32 v68, v6, v7
	global_load_dwordx4 v[28:31], v[4:5], off
	global_load_dwordx4 v[20:23], v[4:5], off offset:64
	global_load_dwordx4 v[12:15], v[4:5], off offset:128
	s_nop 0
	global_load_dwordx4 v[4:7], v[4:5], off offset:192
	v_add_f32_e32 v78, v92, v70
	ds_read_b128 v[70:73], v79
	ds_read_b128 v[74:77], v79 offset:64
	s_waitcnt vmcnt(15) lgkmcnt(1)
	v_mfma_f32_16x16x32_bf16 v[70:73], v[70:73], v[64:67], 0
	s_waitcnt vmcnt(14) lgkmcnt(0)
	v_mfma_f32_16x16x32_bf16 v[70:73], v[74:77], v[60:63], v[70:73]
	ds_read_b128 v[74:77], v79 offset:128
	s_waitcnt vmcnt(13) lgkmcnt(0)
	v_mfma_f32_16x16x32_bf16 v[70:73], v[74:77], v[56:59], v[70:73]
	ds_read_b128 v[74:77], v79 offset:192
	s_waitcnt vmcnt(12) lgkmcnt(0)
	v_mfma_f32_16x16x32_bf16 v[70:73], v[74:77], v[52:55], v[70:73]
	v_lshlrev_b32_e32 v74, 16, v162
	s_nop 6
	v_add_f32_e32 v70, v137, v70
	v_mul_f32_e32 v70, v70, v74
	v_and_b32_e32 v74, 0xffff0000, v162
	v_add_f32_e32 v71, v137, v71
	v_mul_f32_e32 v71, v71, v74
	v_lshlrev_b32_e32 v74, 16, v163
	v_add_f32_e32 v72, v137, v72
	v_mul_f32_e32 v72, v72, v74
	v_and_b32_e32 v74, 0xffff0000, v163
	v_add_f32_e32 v73, v137, v73
	v_mul_f32_e32 v73, v73, v74
	v_mul_f32_e32 v74, v71, v71
	v_mul_f32_e32 v75, v73, v73
	v_fmac_f32_e32 v74, v70, v70
	v_fmac_f32_e32 v75, v72, v72
	v_add_f32_e32 v74, v74, v75
	v_add_f32_e32 v80, v78, v74
	v_cvt_pk_bf16_f32 v71, v70, v71
	v_cvt_pk_bf16_f32 v70, v72, v73
	ds_read_b128 v[72:75], v81
	ds_read_b128 v[76:79], v81 offset:64
	s_waitcnt lgkmcnt(1)
	v_mfma_f32_16x16x32_bf16 v[72:75], v[72:75], v[64:67], 0
	s_waitcnt lgkmcnt(0)
	v_mfma_f32_16x16x32_bf16 v[72:75], v[76:79], v[60:63], v[72:75]
	ds_read_b128 v[76:79], v81 offset:128
	s_waitcnt lgkmcnt(0)
	v_mfma_f32_16x16x32_bf16 v[72:75], v[76:79], v[56:59], v[72:75]
	ds_read_b128 v[76:79], v81 offset:192
	s_waitcnt lgkmcnt(0)
	v_mfma_f32_16x16x32_bf16 v[72:75], v[76:79], v[52:55], v[72:75]
	v_lshlrev_b32_e32 v76, 16, v160
	s_nop 6
	v_add_f32_e32 v72, v137, v72
	v_mul_f32_e32 v72, v72, v76
	v_and_b32_e32 v76, 0xffff0000, v160
	v_add_f32_e32 v73, v137, v73
	v_mul_f32_e32 v73, v73, v76
	v_lshlrev_b32_e32 v76, 16, v161
	v_add_f32_e32 v74, v137, v74
	v_mul_f32_e32 v74, v74, v76
	v_and_b32_e32 v76, 0xffff0000, v161
	v_add_f32_e32 v75, v137, v75
	v_mul_f32_e32 v75, v75, v76
	v_mul_f32_e32 v76, v73, v73
	v_mul_f32_e32 v77, v75, v75
	v_fmac_f32_e32 v76, v72, v72
	v_fmac_f32_e32 v77, v74, v74
	v_add_f32_e32 v76, v76, v77
	v_add_f32_e32 v82, v80, v76
	v_cvt_pk_bf16_f32 v73, v72, v73
	v_cvt_pk_bf16_f32 v72, v74, v75
	ds_read_b128 v[74:77], v83
	ds_read_b128 v[78:81], v83 offset:64
	s_waitcnt lgkmcnt(1)
	v_mfma_f32_16x16x32_bf16 v[74:77], v[74:77], v[64:67], 0
	s_waitcnt lgkmcnt(0)
	v_mfma_f32_16x16x32_bf16 v[74:77], v[78:81], v[60:63], v[74:77]
	ds_read_b128 v[78:81], v83 offset:128
	s_waitcnt lgkmcnt(0)
	v_mfma_f32_16x16x32_bf16 v[74:77], v[78:81], v[56:59], v[74:77]
	ds_read_b128 v[78:81], v83 offset:192
	s_waitcnt lgkmcnt(0)
	v_mfma_f32_16x16x32_bf16 v[74:77], v[78:81], v[52:55], v[74:77]
	v_lshlrev_b32_e32 v78, 16, v158
	v_add_u32_e32 v81, 0x11000, v242
	s_nop 5
	v_add_f32_e32 v74, v137, v74
	v_mul_f32_e32 v74, v74, v78
	v_and_b32_e32 v78, 0xffff0000, v158
	v_add_f32_e32 v75, v137, v75
	v_mul_f32_e32 v75, v75, v78
	v_lshlrev_b32_e32 v78, 16, v159
	v_add_f32_e32 v76, v137, v76
	v_mul_f32_e32 v76, v76, v78
	v_and_b32_e32 v78, 0xffff0000, v159
	v_add_f32_e32 v77, v137, v77
	v_mul_f32_e32 v77, v77, v78
	v_mul_f32_e32 v78, v75, v75
	v_mul_f32_e32 v79, v77, v77
	v_fmac_f32_e32 v78, v74, v74
	v_fmac_f32_e32 v79, v76, v76
	v_add_f32_e32 v78, v78, v79
	v_add_f32_e32 v80, v82, v78
	v_cvt_pk_bf16_f32 v75, v74, v75
	v_cvt_pk_bf16_f32 v74, v76, v77
	ds_read_b128 v[76:79], v81
	s_waitcnt lgkmcnt(0)
	v_mfma_f32_16x16x32_bf16 v[64:67], v[76:79], v[64:67], 0
	ds_read_b128 v[76:79], v81 offset:64
	s_waitcnt lgkmcnt(0)
	v_mfma_f32_16x16x32_bf16 v[60:63], v[76:79], v[60:63], v[64:67]
	s_nop 4
	ds_read_b128 v[64:67], v81 offset:128
	s_waitcnt lgkmcnt(0)
	v_mfma_f32_16x16x32_bf16 v[56:59], v[64:67], v[56:59], v[60:63]
	s_nop 2
	ds_read_b128 v[60:63], v81 offset:192
	v_add_u32_e32 v65, 0x16500, v241
	v_add_u32_e32 v67, 0x17600, v241
	s_waitcnt lgkmcnt(0)
	v_mfma_f32_16x16x32_bf16 v[52:55], v[60:63], v[52:55], v[56:59]
	s_nop 2
	v_lshlrev_b32_e32 v56, 16, v156
	v_add_u32_e32 v63, 0x15400, v241
	s_nop 2
	v_add_f32_e32 v52, v137, v52
	v_mul_f32_e32 v52, v52, v56
	v_and_b32_e32 v56, 0xffff0000, v156
	v_add_f32_e32 v53, v137, v53
	v_mul_f32_e32 v53, v53, v56
	v_lshlrev_b32_e32 v56, 16, v157
	v_add_f32_e32 v54, v137, v54
	v_mul_f32_e32 v54, v54, v56
	v_and_b32_e32 v56, 0xffff0000, v157
	v_add_f32_e32 v55, v137, v55
	v_mul_f32_e32 v55, v55, v56
	v_mul_f32_e32 v56, v53, v53
	v_mul_f32_e32 v57, v55, v55
	v_fmac_f32_e32 v56, v52, v52
	v_fmac_f32_e32 v57, v54, v54
	v_add_f32_e32 v56, v56, v57
	v_add_f32_e32 v62, v80, v56
	v_cvt_pk_bf16_f32 v53, v52, v53
	v_cvt_pk_bf16_f32 v52, v54, v55
	ds_read_b128 v[54:57], v63
	ds_read_b128 v[58:61], v63 offset:64
	s_waitcnt vmcnt(11) lgkmcnt(1)
	v_mfma_f32_16x16x32_bf16 v[54:57], v[54:57], v[48:51], 0
	s_waitcnt vmcnt(10) lgkmcnt(0)
	v_mfma_f32_16x16x32_bf16 v[54:57], v[58:61], v[44:47], v[54:57]
	ds_read_b128 v[58:61], v63 offset:128
	s_waitcnt vmcnt(9) lgkmcnt(0)
	v_mfma_f32_16x16x32_bf16 v[54:57], v[58:61], v[40:43], v[54:57]
	ds_read_b128 v[58:61], v63 offset:192
	s_waitcnt vmcnt(8) lgkmcnt(0)
	v_mfma_f32_16x16x32_bf16 v[54:57], v[58:61], v[32:35], v[54:57]
	v_lshlrev_b32_e32 v58, 16, v154
	s_nop 6
	v_add_f32_e32 v54, v135, v54
	v_mul_f32_e32 v54, v54, v58
	v_and_b32_e32 v58, 0xffff0000, v154
	v_add_f32_e32 v55, v135, v55
	v_mul_f32_e32 v55, v55, v58
	v_lshlrev_b32_e32 v58, 16, v155
	v_add_f32_e32 v56, v135, v56
	v_mul_f32_e32 v56, v56, v58
	v_and_b32_e32 v58, 0xffff0000, v155
	v_add_f32_e32 v57, v135, v57
	v_mul_f32_e32 v57, v57, v58
	v_mul_f32_e32 v58, v55, v55
	v_mul_f32_e32 v59, v57, v57
	v_fmac_f32_e32 v58, v54, v54
	v_fmac_f32_e32 v59, v56, v56
	v_add_f32_e32 v58, v58, v59
	v_add_f32_e32 v64, v62, v58
	v_cvt_pk_bf16_f32 v55, v54, v55
	v_cvt_pk_bf16_f32 v54, v56, v57
	ds_read_b128 v[56:59], v65
	ds_read_b128 v[60:63], v65 offset:64
	s_waitcnt lgkmcnt(1)
	v_mfma_f32_16x16x32_bf16 v[56:59], v[56:59], v[48:51], 0
	s_waitcnt lgkmcnt(0)
	v_mfma_f32_16x16x32_bf16 v[56:59], v[60:63], v[44:47], v[56:59]
	ds_read_b128 v[60:63], v65 offset:128
	s_waitcnt lgkmcnt(0)
	v_mfma_f32_16x16x32_bf16 v[56:59], v[60:63], v[40:43], v[56:59]
	ds_read_b128 v[60:63], v65 offset:192
	s_waitcnt lgkmcnt(0)
	v_mfma_f32_16x16x32_bf16 v[56:59], v[60:63], v[32:35], v[56:59]
	v_lshlrev_b32_e32 v60, 16, v152
	s_nop 6
	v_add_f32_e32 v56, v135, v56
	v_mul_f32_e32 v56, v56, v60
	v_and_b32_e32 v60, 0xffff0000, v152
	v_add_f32_e32 v57, v135, v57
	v_mul_f32_e32 v57, v57, v60
	v_lshlrev_b32_e32 v60, 16, v153
	v_add_f32_e32 v58, v135, v58
	v_mul_f32_e32 v58, v58, v60
	v_and_b32_e32 v60, 0xffff0000, v153
	v_add_f32_e32 v59, v135, v59
	v_mul_f32_e32 v59, v59, v60
	v_mul_f32_e32 v60, v57, v57
	v_mul_f32_e32 v61, v59, v59
	v_fmac_f32_e32 v60, v56, v56
	v_fmac_f32_e32 v61, v58, v58
	v_add_f32_e32 v60, v60, v61
	v_add_f32_e32 v66, v64, v60
	v_cvt_pk_bf16_f32 v57, v56, v57
	v_cvt_pk_bf16_f32 v56, v58, v59
	ds_read_b128 v[58:61], v67
	ds_read_b128 v[62:65], v67 offset:64
	s_waitcnt lgkmcnt(1)
	v_mfma_f32_16x16x32_bf16 v[58:61], v[58:61], v[48:51], 0
	s_waitcnt lgkmcnt(0)
	v_mfma_f32_16x16x32_bf16 v[58:61], v[62:65], v[44:47], v[58:61]
	ds_read_b128 v[62:65], v67 offset:128
	s_waitcnt lgkmcnt(0)
	v_mfma_f32_16x16x32_bf16 v[58:61], v[62:65], v[40:43], v[58:61]
	ds_read_b128 v[62:65], v67 offset:192
	s_waitcnt lgkmcnt(0)
	v_mfma_f32_16x16x32_bf16 v[58:61], v[62:65], v[32:35], v[58:61]
	v_lshlrev_b32_e32 v62, 16, v150
	v_add_u32_e32 v65, 0x15400, v242
	s_nop 5
	v_add_f32_e32 v58, v135, v58
	v_mul_f32_e32 v58, v58, v62
	v_and_b32_e32 v62, 0xffff0000, v150
	v_add_f32_e32 v59, v135, v59
	v_mul_f32_e32 v59, v59, v62
	v_lshlrev_b32_e32 v62, 16, v151
	v_add_f32_e32 v60, v135, v60
	v_mul_f32_e32 v60, v60, v62
	v_and_b32_e32 v62, 0xffff0000, v151
	v_add_f32_e32 v61, v135, v61
	v_mul_f32_e32 v61, v61, v62
	v_mul_f32_e32 v62, v59, v59
	v_mul_f32_e32 v63, v61, v61
	v_fmac_f32_e32 v62, v58, v58
	v_fmac_f32_e32 v63, v60, v60
	v_add_f32_e32 v62, v62, v63
	v_add_f32_e32 v64, v66, v62
	v_cvt_pk_bf16_f32 v59, v58, v59
	v_cvt_pk_bf16_f32 v58, v60, v61
	ds_read_b128 v[60:63], v65
	s_waitcnt lgkmcnt(0)
	v_mfma_f32_16x16x32_bf16 v[48:51], v[60:63], v[48:51], 0
	ds_read_b128 v[60:63], v65 offset:64
	s_waitcnt lgkmcnt(0)
	v_mfma_f32_16x16x32_bf16 v[44:47], v[60:63], v[44:47], v[48:51]
	s_nop 4
	ds_read_b128 v[48:51], v65 offset:128
	s_waitcnt lgkmcnt(0)
	v_mfma_f32_16x16x32_bf16 v[40:43], v[48:51], v[40:43], v[44:47]
	s_nop 2
	ds_read_b128 v[44:47], v65 offset:192
	v_add_u32_e32 v49, 0x1a900, v241
	v_add_u32_e32 v51, 0x1ba00, v241
	s_waitcnt lgkmcnt(0)
	v_mfma_f32_16x16x32_bf16 v[32:35], v[44:47], v[32:35], v[40:43]
	s_nop 2
	v_lshlrev_b32_e32 v40, 16, v148
	s_nop 3
	v_add_f32_e32 v32, v135, v32
	v_mul_f32_e32 v32, v32, v40
	v_and_b32_e32 v40, 0xffff0000, v148
	v_add_f32_e32 v33, v135, v33
	v_mul_f32_e32 v33, v33, v40
	v_lshlrev_b32_e32 v40, 16, v149
	v_add_f32_e32 v34, v135, v34
	v_mul_f32_e32 v34, v34, v40
	v_and_b32_e32 v40, 0xffff0000, v149
	v_add_f32_e32 v35, v135, v35
	v_mul_f32_e32 v35, v35, v40
	v_mul_f32_e32 v40, v33, v33
	v_mul_f32_e32 v41, v35, v35
	v_fmac_f32_e32 v40, v32, v32
	v_fmac_f32_e32 v41, v34, v34
	v_add_f32_e32 v40, v40, v41
	v_cvt_pk_bf16_f32 v33, v32, v33
	v_cvt_pk_bf16_f32 v32, v34, v35
	v_add_u32_e32 v34, 0x19800, v241
	v_add_f32_e32 v48, v64, v40
	ds_read_b128 v[40:43], v34
	ds_read_b128 v[44:47], v34 offset:64
	s_waitcnt vmcnt(7) lgkmcnt(1)
	v_mfma_f32_16x16x32_bf16 v[40:43], v[40:43], v[36:39], 0
	s_waitcnt vmcnt(6) lgkmcnt(0)
	v_mfma_f32_16x16x32_bf16 v[40:43], v[44:47], v[24:27], v[40:43]
	ds_read_b128 v[44:47], v34 offset:128
	s_waitcnt vmcnt(5) lgkmcnt(0)
	v_mfma_f32_16x16x32_bf16 v[40:43], v[44:47], v[16:19], v[40:43]
	ds_read_b128 v[44:47], v34 offset:192
	v_lshlrev_b32_e32 v34, 16, v146
	s_waitcnt vmcnt(4) lgkmcnt(0)
	v_mfma_f32_16x16x32_bf16 v[40:43], v[44:47], v[8:11], v[40:43]
	s_nop 7
	v_add_f32_e32 v35, v133, v40
	v_mul_f32_e32 v34, v35, v34
	v_and_b32_e32 v35, 0xffff0000, v146
	v_add_f32_e32 v40, v133, v41
	v_mul_f32_e32 v35, v40, v35
	v_lshlrev_b32_e32 v40, 16, v147
	v_add_f32_e32 v41, v133, v42
	v_mul_f32_e32 v40, v41, v40
	v_and_b32_e32 v41, 0xffff0000, v147
	v_add_f32_e32 v42, v133, v43
	v_mul_f32_e32 v41, v42, v41
	v_mul_f32_e32 v42, v35, v35
	v_mul_f32_e32 v43, v41, v41
	v_fmac_f32_e32 v42, v34, v34
	v_fmac_f32_e32 v43, v40, v40
	v_add_f32_e32 v42, v42, v43
	v_add_f32_e32 v48, v48, v42
	v_cvt_pk_bf16_f32 v35, v34, v35
	v_cvt_pk_bf16_f32 v34, v40, v41
	ds_read_b128 v[40:43], v49
	ds_read_b128 v[44:47], v49 offset:64
	s_waitcnt lgkmcnt(1)
	v_mfma_f32_16x16x32_bf16 v[40:43], v[40:43], v[36:39], 0
	s_waitcnt lgkmcnt(0)
	v_mfma_f32_16x16x32_bf16 v[40:43], v[44:47], v[24:27], v[40:43]
	ds_read_b128 v[44:47], v49 offset:128
	s_waitcnt lgkmcnt(0)
	v_mfma_f32_16x16x32_bf16 v[40:43], v[44:47], v[16:19], v[40:43]
	ds_read_b128 v[44:47], v49 offset:192
	s_waitcnt lgkmcnt(0)
	v_mfma_f32_16x16x32_bf16 v[40:43], v[44:47], v[8:11], v[40:43]
	v_lshlrev_b32_e32 v44, 16, v144
	s_nop 6
	v_add_f32_e32 v40, v133, v40
	v_mul_f32_e32 v40, v40, v44
	v_and_b32_e32 v44, 0xffff0000, v144
	v_add_f32_e32 v41, v133, v41
	v_mul_f32_e32 v41, v41, v44
	v_lshlrev_b32_e32 v44, 16, v145
	v_add_f32_e32 v42, v133, v42
	v_mul_f32_e32 v42, v42, v44
	v_and_b32_e32 v44, 0xffff0000, v145
	v_add_f32_e32 v43, v133, v43
	v_mul_f32_e32 v43, v43, v44
	v_mul_f32_e32 v44, v41, v41
	v_mul_f32_e32 v45, v43, v43
	v_fmac_f32_e32 v44, v40, v40
	v_fmac_f32_e32 v45, v42, v42
	v_add_f32_e32 v44, v44, v45
	v_add_f32_e32 v50, v48, v44
	v_cvt_pk_bf16_f32 v41, v40, v41
	v_cvt_pk_bf16_f32 v40, v42, v43
	ds_read_b128 v[42:45], v51
	ds_read_b128 v[46:49], v51 offset:64
	s_waitcnt lgkmcnt(1)
	v_mfma_f32_16x16x32_bf16 v[42:45], v[42:45], v[36:39], 0
	s_waitcnt lgkmcnt(0)
	v_mfma_f32_16x16x32_bf16 v[42:45], v[46:49], v[24:27], v[42:45]
	ds_read_b128 v[46:49], v51 offset:128
	s_waitcnt lgkmcnt(0)
	v_mfma_f32_16x16x32_bf16 v[42:45], v[46:49], v[16:19], v[42:45]
	ds_read_b128 v[46:49], v51 offset:192
	s_waitcnt lgkmcnt(0)
	v_mfma_f32_16x16x32_bf16 v[42:45], v[46:49], v[8:11], v[42:45]
	v_lshlrev_b32_e32 v46, 16, v142
	v_add_u32_e32 v49, 0x19800, v242
	s_nop 5
	v_add_f32_e32 v42, v133, v42
	v_mul_f32_e32 v42, v42, v46
	v_and_b32_e32 v46, 0xffff0000, v142
	v_add_f32_e32 v43, v133, v43
	v_mul_f32_e32 v43, v43, v46
	v_lshlrev_b32_e32 v46, 16, v143
	v_add_f32_e32 v44, v133, v44
	v_mul_f32_e32 v44, v44, v46
	v_and_b32_e32 v46, 0xffff0000, v143
	v_add_f32_e32 v45, v133, v45
	v_mul_f32_e32 v45, v45, v46
	v_mul_f32_e32 v46, v43, v43
	v_mul_f32_e32 v47, v45, v45
	v_fmac_f32_e32 v46, v42, v42
	v_fmac_f32_e32 v47, v44, v44
	v_add_f32_e32 v46, v46, v47
	v_add_f32_e32 v48, v50, v46
	v_cvt_pk_bf16_f32 v43, v42, v43
	v_cvt_pk_bf16_f32 v42, v44, v45
	ds_read_b128 v[44:47], v49
	s_waitcnt lgkmcnt(0)
	v_mfma_f32_16x16x32_bf16 v[36:39], v[44:47], v[36:39], 0
	ds_read_b128 v[44:47], v49 offset:64
	s_waitcnt lgkmcnt(0)
	v_mfma_f32_16x16x32_bf16 v[24:27], v[44:47], v[24:27], v[36:39]
	s_nop 4
	ds_read_b128 v[36:39], v49 offset:128
	s_waitcnt lgkmcnt(0)
	v_mfma_f32_16x16x32_bf16 v[16:19], v[36:39], v[16:19], v[24:27]
	s_nop 2
	ds_read_b128 v[24:27], v49 offset:192
	v_add_u32_e32 v37, 0x1ed00, v241
	s_waitcnt lgkmcnt(0)
	v_mfma_f32_16x16x32_bf16 v[8:11], v[24:27], v[8:11], v[16:19]
	s_nop 2
	v_lshlrev_b32_e32 v16, 16, v140
	s_nop 3
	v_add_f32_e32 v8, v133, v8
	v_mul_f32_e32 v8, v8, v16
	v_and_b32_e32 v16, 0xffff0000, v140
	v_add_f32_e32 v9, v133, v9
	v_mul_f32_e32 v9, v9, v16
	v_lshlrev_b32_e32 v16, 16, v141
	v_add_f32_e32 v10, v133, v10
	v_mul_f32_e32 v10, v10, v16
	v_and_b32_e32 v16, 0xffff0000, v141
	v_add_f32_e32 v11, v133, v11
	v_mul_f32_e32 v11, v11, v16
	v_mul_f32_e32 v16, v9, v9
	v_mul_f32_e32 v17, v11, v11
	v_fmac_f32_e32 v16, v8, v8
	v_fmac_f32_e32 v17, v10, v10
	v_add_f32_e32 v16, v16, v17
	v_cvt_pk_bf16_f32 v9, v8, v9
	v_cvt_pk_bf16_f32 v8, v10, v11
	v_add_u32_e32 v10, 0x1dc00, v241
	v_add_f32_e32 v36, v48, v16
	ds_read_b128 v[16:19], v10
	ds_read_b128 v[24:27], v10 offset:64
	s_waitcnt vmcnt(3) lgkmcnt(1)
	v_mfma_f32_16x16x32_bf16 v[16:19], v[16:19], v[28:31], 0
	s_waitcnt vmcnt(2) lgkmcnt(0)
	v_mfma_f32_16x16x32_bf16 v[16:19], v[24:27], v[20:23], v[16:19]
	ds_read_b128 v[24:27], v10 offset:128
	s_waitcnt vmcnt(1) lgkmcnt(0)
	v_mfma_f32_16x16x32_bf16 v[16:19], v[24:27], v[12:15], v[16:19]
	ds_read_b128 v[24:27], v10 offset:192
	v_lshlrev_b32_e32 v10, 16, v138
	s_waitcnt vmcnt(0) lgkmcnt(0)
	v_mfma_f32_16x16x32_bf16 v[16:19], v[24:27], v[4:7], v[16:19]
	s_nop 7
	v_add_f32_e32 v11, v99, v16
	v_mul_f32_e32 v10, v11, v10
	v_and_b32_e32 v11, 0xffff0000, v138
	v_add_f32_e32 v16, v99, v17
	v_mul_f32_e32 v11, v16, v11
	v_lshlrev_b32_e32 v16, 16, v139
	v_add_f32_e32 v17, v99, v18
	v_mul_f32_e32 v16, v17, v16
	v_and_b32_e32 v17, 0xffff0000, v139
	v_add_f32_e32 v18, v99, v19
	v_mul_f32_e32 v17, v18, v17
	v_mul_f32_e32 v18, v11, v11
	v_mul_f32_e32 v19, v17, v17
	v_fmac_f32_e32 v18, v10, v10
	v_fmac_f32_e32 v19, v16, v16
	v_add_f32_e32 v18, v18, v19
	v_add_f32_e32 v36, v36, v18
	v_cvt_pk_bf16_f32 v11, v10, v11
	v_cvt_pk_bf16_f32 v10, v16, v17
	ds_read_b128 v[16:19], v37
	ds_read_b128 v[24:27], v37 offset:64
	s_waitcnt lgkmcnt(1)
	v_mfma_f32_16x16x32_bf16 v[16:19], v[16:19], v[28:31], 0
	s_waitcnt lgkmcnt(0)
	v_mfma_f32_16x16x32_bf16 v[16:19], v[24:27], v[20:23], v[16:19]
	ds_read_b128 v[24:27], v37 offset:128
	s_waitcnt lgkmcnt(0)
	v_mfma_f32_16x16x32_bf16 v[16:19], v[24:27], v[12:15], v[16:19]
	ds_read_b128 v[24:27], v37 offset:192
	s_waitcnt lgkmcnt(0)
	v_mfma_f32_16x16x32_bf16 v[16:19], v[24:27], v[4:7], v[16:19]
	v_lshlrev_b32_e32 v24, 16, v120
	s_nop 6
	v_add_f32_e32 v16, v99, v16
	v_mul_f32_e32 v16, v16, v24
	v_and_b32_e32 v24, 0xffff0000, v120
	v_add_f32_e32 v17, v99, v17
	v_mul_f32_e32 v17, v17, v24
	v_lshlrev_b32_e32 v24, 16, v121
	v_add_f32_e32 v18, v99, v18
	v_mul_f32_e32 v18, v18, v24
	v_and_b32_e32 v24, 0xffff0000, v121
	v_add_f32_e32 v19, v99, v19
	v_mul_f32_e32 v19, v19, v24
	v_mul_f32_e32 v24, v17, v17
	v_mul_f32_e32 v25, v19, v19
	v_fmac_f32_e32 v24, v16, v16
	v_fmac_f32_e32 v25, v18, v18
	v_add_f32_e32 v24, v24, v25
	v_cvt_pk_bf16_f32 v17, v16, v17
	v_cvt_pk_bf16_f32 v16, v18, v19
	v_add_u32_e32 v18, 0x1fe00, v241
	v_add_f32_e32 v44, v36, v24
	ds_read_b128 v[24:27], v18
	ds_read_b128 v[36:39], v18 offset:64
	s_waitcnt lgkmcnt(1)
	v_mfma_f32_16x16x32_bf16 v[24:27], v[24:27], v[28:31], 0
	s_waitcnt lgkmcnt(0)
	v_mfma_f32_16x16x32_bf16 v[24:27], v[36:39], v[20:23], v[24:27]
	ds_read_b128 v[36:39], v18 offset:128
	s_waitcnt lgkmcnt(0)
	v_mfma_f32_16x16x32_bf16 v[24:27], v[36:39], v[12:15], v[24:27]
	ds_read_b128 v[36:39], v18 offset:192
	v_lshlrev_b32_e32 v18, 16, v118
	s_waitcnt lgkmcnt(0)
	v_mfma_f32_16x16x32_bf16 v[24:27], v[36:39], v[4:7], v[24:27]
	v_add_u32_e32 v37, 0x1dc00, v242
	s_nop 6
	v_add_f32_e32 v19, v99, v24
	v_mul_f32_e32 v18, v19, v18
	v_and_b32_e32 v19, 0xffff0000, v118
	v_add_f32_e32 v24, v99, v25
	v_mul_f32_e32 v19, v24, v19
	v_lshlrev_b32_e32 v24, 16, v119
	v_add_f32_e32 v25, v99, v26
	v_mul_f32_e32 v24, v25, v24
	v_and_b32_e32 v25, 0xffff0000, v119
	v_add_f32_e32 v26, v99, v27
	v_mul_f32_e32 v25, v26, v25
	v_mul_f32_e32 v26, v19, v19
	v_mul_f32_e32 v27, v25, v25
	v_fmac_f32_e32 v26, v18, v18
	v_fmac_f32_e32 v27, v24, v24
	v_add_f32_e32 v26, v26, v27
	v_add_f32_e32 v36, v44, v26
	v_cvt_pk_bf16_f32 v19, v18, v19
	v_cvt_pk_bf16_f32 v18, v24, v25
	ds_read_b128 v[24:27], v37
	s_waitcnt lgkmcnt(0)
	v_mfma_f32_16x16x32_bf16 v[24:27], v[24:27], v[28:31], 0
	ds_read_b128 v[28:31], v37 offset:64
	s_waitcnt lgkmcnt(0)
	v_mfma_f32_16x16x32_bf16 v[20:23], v[28:31], v[20:23], v[24:27]
	s_nop 4
	ds_read_b128 v[24:27], v37 offset:128
	s_waitcnt lgkmcnt(0)
	v_mfma_f32_16x16x32_bf16 v[12:15], v[24:27], v[12:15], v[20:23]
	s_nop 2
	ds_read_b128 v[20:23], v37 offset:192
	s_waitcnt lgkmcnt(0)
	v_mfma_f32_16x16x32_bf16 v[4:7], v[20:23], v[4:7], v[12:15]
	s_nop 2
	v_lshlrev_b32_e32 v12, 16, v116
	s_nop 3
	v_add_f32_e32 v4, v99, v4
	v_mul_f32_e32 v4, v4, v12
	v_and_b32_e32 v12, 0xffff0000, v116
	v_add_f32_e32 v5, v99, v5
	v_mul_f32_e32 v5, v5, v12
	v_lshlrev_b32_e32 v12, 16, v117
	v_add_f32_e32 v6, v99, v6
	v_mul_f32_e32 v6, v6, v12
	v_and_b32_e32 v12, 0xffff0000, v117
	v_add_f32_e32 v7, v99, v7
	v_mul_f32_e32 v7, v7, v12
	v_mul_f32_e32 v12, v5, v5
	v_mul_f32_e32 v13, v7, v7
	v_fmac_f32_e32 v12, v4, v4
	v_fmac_f32_e32 v13, v6, v6
	v_add_f32_e32 v12, v12, v13
	v_add_f32_e32 v12, v36, v12
	v_cvt_pk_bf16_f32 v5, v4, v5
	v_cvt_pk_bf16_f32 v4, v6, v7
	ds_bpermute_b32 v6, v129, v12
	s_waitcnt lgkmcnt(0)
	v_add_f32_e32 v6, v12, v6
	ds_bpermute_b32 v7, v131, v6
	s_and_saveexec_b64 s[8:9], vcc
	s_cbranch_execz .LBB0_368
	v_rsq_f32_e32 v14, v3
	v_lshl_add_u64 v[12:13], v[0:1], 2, s[6:7]
	v_add_co_u32_e32 v12, vcc, 0x1a00000, v12
	s_nop 1
	v_addc_co_u32_e32 v13, vcc, 0, v13, vcc
	global_store_dword v[12:13], v14, off
	s_branch .LBB0_368
